# speedup vs baseline: 1.0169x; 1.0169x over previous
; __global__ __launch_bounds__(512, 2) void mega(Params p_arg, int lo, int hi) {
;   __shared__ __attribute__((aligned(1024))) char shm[131072 + 2048];
;   cg::grid_group grid = cg::this_grid();
;   int rep_done = 0;
;   const int wave_sg = __builtin_amdgcn_readfirstlane((int)(threadIdx.x >> 6));
;   for (int ph = lo; ph < hi; ++ph) {
;     int opcode = 15;
;     int wvl_ = wave_sg;
;     asm volatile("" : "+s"(wvl_));
;     int TID_ = (wvl_ << 6) | (int)__builtin_amdgcn_mbcnt_hi(~0u, __builtin_amdgcn_mbcnt_lo(~0u, 0u));
;     int BID_ = __builtin_amdgcn_workgroup_id_x();
;     asm volatile("" : "+v"(TID_));
;     asm volatile("" : "+s"(BID_));
;     CParams* pptr = (CParams*)__builtin_amdgcn_kernarg_segment_ptr();
;     asm volatile("" : "+s"(pptr));
;     PREF p = *pptr;
;     char* ws = p.ws;
;     int kind = -1, g = 0, layer = 0, step = 0;
.LBB0_1:
	s_load_dword s66, s[0:1], 0xf0
	s_add_u32 s64, s0, 0xf0
	s_addc_u32 s65, s1, 0
	s_mov_b32 s69, 0
	s_mov_b32 s67, s69
	v_writelane_b32 v236, s69, 63
	s_waitcnt lgkmcnt(0)
	s_cmpk_eq_i32 s66, 0x100
	s_cselect_b64 s[4:5], -1, 0
	v_writelane_b32 v236, s4, 0
	s_cmpk_lg_i32 s66, 0x100
	v_lshrrev_b32_e32 v2, 20, v0
	v_writelane_b32 v236, s5, 1
	s_cselect_b64 s[4:5], -1, 0
	v_writelane_b32 v236, s4, 2
	s_lshr_b32 s48, s2, 6
	s_lshl_b64 s[50:51], s[66:67], 9
	v_writelane_b32 v236, s5, 3
	v_writelane_b32 v236, s91, 4
	v_writelane_b32 v236, s0, 5
	v_lshrrev_b32_e32 v0, 10, v0
	s_lshr_b32 s49, s66, 3
	v_writelane_b32 v236, s1, 6
	v_writelane_b32 v236, s48, 7
	s_lshl_b32 s67, s66, 3
	s_sub_i32 s2, s59, s58
	v_or_b32_e32 v0, v0, v2
	v_writelane_b32 v236, s50, 8
	s_cmp_gt_i32 s2, 1
	v_and_or_b32 v0, v0, s94, v1
	v_writelane_b32 v236, s51, 9
	s_cselect_b64 s[52:53], -1, 0
	v_cmp_eq_u32_e64 s[54:55], 0, v0
	v_mbcnt_lo_u32_b32 v0, -1, 0
	v_writelane_b32 v236, s49, 10
	v_mbcnt_hi_u32_b32 v203, -1, v0
	v_writelane_b32 v236, s52, 11
	s_mov_b32 s80, 0x6dc9c883
	v_and_b32_e32 v0, 64, v203
	v_writelane_b32 v236, s53, 12
	s_movk_i32 s47, 0x100
	v_mov_b32_e32 v197, 0
	s_movk_i32 s77, 0x110
	s_movk_i32 s33, 0x4400
	s_movk_i32 s86, 0x1800
	s_mov_b64 s[78:79], 0x1000
	s_movk_i32 s87, 0x1000
	s_mov_b32 s82, 0xb000
	s_mov_b32 s83, 0x10000
	s_movk_i32 s62, 0x3fff
	s_movk_i32 s63, 0xa0
	s_movk_i32 s56, 0x800
	s_movk_i32 s57, 0x90
	v_mov_b32_e32 v200, 0x3a27c5ac
	s_mov_b32 s95, 0x800000
	s_mov_b32 s96, 0x3f317217
	s_mov_b32 s97, 0x7f800000
	v_mov_b32_e32 v201, 0x358637bd
	s_mov_b32 s70, 0xca01000
	s_movk_i32 s71, 0x3000
	v_mov_b32_e32 v202, 0x260
	s_movk_i32 s31, 0x104
	s_mov_b32 s76, 0x8580
	s_movk_i32 s72, 0x2c00
	s_mov_b32 s81, 0x3fc45f30
	v_xor_b32_e32 v204, 16, v203
	v_add_u32_e32 v205, 64, v0
	v_xor_b32_e32 v206, 32, v203
	v_mov_b32_e32 v207, 0xff800000
	v_mov_b32_e32 v208, 0x15800
	v_mov_b32_e32 v209, 0x41b17218
	v_mov_b32_e32 v210, 0x14000
	v_mov_b32_e32 v211, 0x15000
	v_not_b32_e32 v212, 31
	s_mov_b64 s[34:35], 0x10ab3c00
	s_mov_b64 s[2:3], 0x2800
	v_writelane_b32 v236, s54, 13
	s_nop 1
	v_writelane_b32 v236, s55, 14
	s_branch .LBB0_6

; DEVI float bf2f(u16 h) { return __uint_as_float(((unsigned)h) << 16); }
; DEVI float sigm(float x) { return 1.f / (1.f + __expf(-x)); }
; DEVI void hgrn_c_item(int TID_, int BID_, PREF p, int item, char* shm) {
;     ...
;     float run = 0.f;
; #pragma unroll 8
;     for (int s = 0; s < 64; ++s) {
;       const int i = dir == 0 ? s : 63 - s;
;       float f = lbv + (1.f - lbv) * sigm(bf2f(kc[i * 136]));
;       run += __logf(f);
;       qc[i * 136] = f2bf(bf2f(qc[i * 136]) * __expf(run));
;       kc[i * 136] = f2bf((1.f - f) * __expf(-run));
;     }
.LBB0_107:
	s_add_i32 s10, s68, 7
	s_add_i32 s11, s61, 0
	v_mov_b32_e32 v179, s10
	v_mov_b32_e32 v238, s11
	v_cndmask_b32_e64 v179, v179, v238, s[6:7]
	v_mad_u32_u24 v237, v179, s77, v86
	ds_read_u16 v228, v237 offset:34816
	ds_read_u16 v227, v237
	s_add_i32 s10, s68, 6
	s_add_i32 s11, s61, 1
	v_mov_b32_e32 v179, s10
	v_mov_b32_e32 v238, s11
	v_cndmask_b32_e64 v179, v179, v238, s[6:7]
	v_mad_u32_u24 v235, v179, s77, v86
	ds_read_u16 v226, v235 offset:34816
	ds_read_u16 v225, v235
	s_add_i32 s10, s68, 5
	s_add_i32 s11, s61, 2
	v_mov_b32_e32 v179, s10
	v_mov_b32_e32 v238, s11
	v_cndmask_b32_e64 v179, v179, v238, s[6:7]
	v_mad_u32_u24 v234, v179, s77, v86
	ds_read_u16 v224, v234 offset:34816
	ds_read_u16 v223, v234
	s_add_i32 s10, s68, 4
	s_add_i32 s11, s61, 3
	v_mov_b32_e32 v179, s10
	v_mov_b32_e32 v238, s11
	v_cndmask_b32_e64 v179, v179, v238, s[6:7]
	v_mad_u32_u24 v233, v179, s77, v86
	ds_read_u16 v222, v233 offset:34816
	ds_read_u16 v221, v233
	s_add_i32 s10, s68, 3
	s_add_i32 s11, s61, 4
	v_mov_b32_e32 v179, s10
	v_mov_b32_e32 v238, s11
	v_cndmask_b32_e64 v179, v179, v238, s[6:7]
	v_mad_u32_u24 v232, v179, s77, v86
	ds_read_u16 v220, v232 offset:34816
	ds_read_u16 v219, v232
	s_add_i32 s10, s68, 2
	s_add_i32 s11, s61, 5
	v_mov_b32_e32 v179, s10
	v_mov_b32_e32 v238, s11
	v_cndmask_b32_e64 v179, v179, v238, s[6:7]
	v_mad_u32_u24 v231, v179, s77, v86
	ds_read_u16 v218, v231 offset:34816
	ds_read_u16 v217, v231
	s_add_i32 s10, s68, 1
	s_add_i32 s11, s61, 6
	v_mov_b32_e32 v179, s10
	v_mov_b32_e32 v238, s11
	v_cndmask_b32_e64 v179, v179, v238, s[6:7]
	v_mad_u32_u24 v230, v179, s77, v86
	ds_read_u16 v216, v230 offset:34816
	ds_read_u16 v215, v230
	s_add_i32 s10, s68, 0
	s_add_i32 s11, s61, 7
	v_mov_b32_e32 v179, s10
	v_mov_b32_e32 v238, s11
	v_cndmask_b32_e64 v179, v179, v238, s[6:7]
	v_mad_u32_u24 v229, v179, s77, v86
	ds_read_u16 v214, v229 offset:34816
	ds_read_u16 v213, v229
	s_waitcnt lgkmcnt(0)
	s_add_i32 s10, s68, 7
	v_mov_b32_e32 v3, s10
	v_mov_b32_e32 v4, s61
	v_cndmask_b32_e64 v3, v3, v4, s[6:7]
	v_mad_u64_u32 v[4:5], s[10:11], v3, s77, v[86:87]
	v_mov_b32_e32 v3, v228
	s_waitcnt lgkmcnt(0)
	v_lshlrev_b32_e32 v3, 16, v3
	v_mul_f32_e32 v3, 0xbfb8aa3b, v3
	v_exp_f32_e32 v3, v3
	s_nop 0
	v_add_f32_e32 v3, 1.0, v3
	v_div_scale_f32 v5, s[10:11], v3, v3, 1.0
	v_rcp_f32_e32 v6, v5
	s_add_i32 s10, s68, 6
	s_add_i32 s11, s61, 1
	v_fma_f32 v7, -v5, v6, 1.0
	v_fmac_f32_e32 v6, v7, v6
	v_div_scale_f32 v7, vcc, 1.0, v3, 1.0
	v_mul_f32_e32 v8, v7, v6
	v_fma_f32 v9, -v5, v8, v7
	v_fmac_f32_e32 v8, v9, v6
	v_fma_f32 v5, -v5, v8, v7
	v_div_fmas_f32 v5, v5, v6, v8
	v_div_fixup_f32 v3, v5, v3, 1.0
	v_fma_f32 v3, v1, v3, v0
	v_cmp_gt_f32_e32 vcc, s95, v3
	s_nop 1
	v_cndmask_b32_e64 v5, 0, 32, vcc
	v_ldexp_f32 v5, v3, v5
	v_log_f32_e32 v5, v5
	s_nop 0
	v_mul_f32_e32 v6, 0x3f317217, v5
	v_fma_f32 v6, v5, s96, -v6
	v_fmac_f32_e32 v6, 0x3377d1cf, v5
	v_fmac_f32_e32 v6, 0x3f317217, v5
	v_cmp_lt_f32_e64 s[42:43], |v5|, s97
	s_nop 1
	v_cndmask_b32_e64 v5, v5, v6, s[42:43]
	v_cndmask_b32_e32 v6, 0, v209, vcc
	v_sub_f32_e32 v5, v5, v6
	v_add_f32_e32 v5, v2, v5
	v_mov_b32_e32 v2, v227
	v_mul_f32_e32 v6, 0x3fb8aa3b, v5
	v_exp_f32_e32 v6, v6
	s_waitcnt lgkmcnt(0)
	v_lshlrev_b32_e32 v2, 16, v2
	v_mul_f32_e32 v2, v6, v2
	v_cvt_pk_bf16_f32 v2, v2, s0
	ds_write_b16 v4, v2
	v_sub_f32_e32 v2, 1.0, v3
	v_mul_f32_e32 v3, 0xbfb8aa3b, v5
	v_exp_f32_e32 v3, v3
	s_nop 0
	v_mul_f32_e32 v2, v2, v3
	v_cvt_pk_bf16_f32 v2, v2, s0
	ds_write_b16 v4, v2 offset:34816
	v_mov_b32_e32 v2, s10
	v_mov_b32_e32 v3, s11
	v_cndmask_b32_e64 v2, v2, v3, s[6:7]
	v_mad_u64_u32 v[2:3], s[10:11], v2, s77, v[86:87]
	v_mov_b32_e32 v3, v226
	s_waitcnt lgkmcnt(0)
	v_lshlrev_b32_e32 v3, 16, v3
	v_mul_f32_e32 v3, 0xbfb8aa3b, v3
	v_exp_f32_e32 v3, v3
	s_nop 0
	v_add_f32_e32 v3, 1.0, v3
	v_div_scale_f32 v4, s[10:11], v3, v3, 1.0
	v_rcp_f32_e32 v6, v4
	s_add_i32 s10, s68, 5
	s_add_i32 s11, s61, 2
	v_fma_f32 v7, -v4, v6, 1.0
	v_fmac_f32_e32 v6, v7, v6
	v_div_scale_f32 v7, vcc, 1.0, v3, 1.0
	v_mul_f32_e32 v8, v7, v6
	v_fma_f32 v9, -v4, v8, v7
	v_fmac_f32_e32 v8, v9, v6
	v_fma_f32 v4, -v4, v8, v7
	v_div_fmas_f32 v4, v4, v6, v8
	v_div_fixup_f32 v3, v4, v3, 1.0
	v_fma_f32 v3, v1, v3, v0
	v_cmp_gt_f32_e32 vcc, s95, v3
	s_nop 1
	v_cndmask_b32_e64 v4, 0, 32, vcc
	v_ldexp_f32 v4, v3, v4
	v_log_f32_e32 v4, v4
	v_sub_f32_e32 v3, 1.0, v3
	v_mul_f32_e32 v6, 0x3f317217, v4
	v_fma_f32 v6, v4, s96, -v6
	v_fmac_f32_e32 v6, 0x3377d1cf, v4
	v_fmac_f32_e32 v6, 0x3f317217, v4
	v_cmp_lt_f32_e64 s[42:43], |v4|, s97
	s_nop 1
	v_cndmask_b32_e64 v4, v4, v6, s[42:43]
	v_cndmask_b32_e32 v6, 0, v209, vcc
	v_sub_f32_e32 v4, v4, v6
	v_add_f32_e32 v4, v5, v4
	v_mov_b32_e32 v5, v225
	v_mul_f32_e32 v6, 0x3fb8aa3b, v4
	v_exp_f32_e32 v6, v6
	s_waitcnt lgkmcnt(0)
	v_lshlrev_b32_e32 v5, 16, v5
	v_mul_f32_e32 v5, v6, v5
	v_cvt_pk_bf16_f32 v5, v5, s0
	ds_write_b16 v2, v5
	v_mul_f32_e32 v5, 0xbfb8aa3b, v4
	v_exp_f32_e32 v5, v5
	s_nop 0
	v_mul_f32_e32 v3, v3, v5
	v_cvt_pk_bf16_f32 v3, v3, s0
	ds_write_b16 v2, v3 offset:34816
	v_mov_b32_e32 v2, s10
	v_mov_b32_e32 v3, s11
	v_cndmask_b32_e64 v2, v2, v3, s[6:7]
	v_mad_u64_u32 v[2:3], s[10:11], v2, s77, v[86:87]
	v_mov_b32_e32 v3, v224
	s_waitcnt lgkmcnt(0)
; DEVI float bf2f(u16 h) { return __uint_as_float(((unsigned)h) << 16); }
; DEVI float sigm(float x) { return 1.f / (1.f + __expf(-x)); }
; DEVI void hgrn_c_item(int TID_, int BID_, PREF p, int item, char* shm) {
;     ...
;     float run = 0.f;
; #pragma unroll 8
;     for (int s = 0; s < 64; ++s) {
;       const int i = dir == 0 ? s : 63 - s;
;       float f = lbv + (1.f - lbv) * sigm(bf2f(kc[i * 136]));
;       run += __logf(f);
;       qc[i * 136] = f2bf(bf2f(qc[i * 136]) * __expf(run));
;       kc[i * 136] = f2bf((1.f - f) * __expf(-run));
;     }
	v_lshlrev_b32_e32 v3, 16, v3
	v_mul_f32_e32 v3, 0xbfb8aa3b, v3
	v_exp_f32_e32 v3, v3
	s_nop 0
	v_add_f32_e32 v3, 1.0, v3
	v_div_scale_f32 v5, s[10:11], v3, v3, 1.0
	v_rcp_f32_e32 v6, v5
	s_add_i32 s10, s68, 4
	s_add_i32 s11, s61, 3
	v_fma_f32 v7, -v5, v6, 1.0
	v_fmac_f32_e32 v6, v7, v6
	v_div_scale_f32 v7, vcc, 1.0, v3, 1.0
	v_mul_f32_e32 v8, v7, v6
	v_fma_f32 v9, -v5, v8, v7
	v_fmac_f32_e32 v8, v9, v6
	v_fma_f32 v5, -v5, v8, v7
	v_div_fmas_f32 v5, v5, v6, v8
	v_div_fixup_f32 v3, v5, v3, 1.0
	v_fma_f32 v3, v1, v3, v0
	v_cmp_gt_f32_e32 vcc, s95, v3
	s_nop 1
	v_cndmask_b32_e64 v5, 0, 32, vcc
	v_ldexp_f32 v5, v3, v5
	v_log_f32_e32 v5, v5
	v_sub_f32_e32 v3, 1.0, v3
	v_mul_f32_e32 v6, 0x3f317217, v5
	v_fma_f32 v6, v5, s96, -v6
	v_fmac_f32_e32 v6, 0x3377d1cf, v5
	v_fmac_f32_e32 v6, 0x3f317217, v5
	v_cmp_lt_f32_e64 s[42:43], |v5|, s97
	s_nop 1
	v_cndmask_b32_e64 v5, v5, v6, s[42:43]
	v_cndmask_b32_e32 v6, 0, v209, vcc
	v_sub_f32_e32 v5, v5, v6
	v_add_f32_e32 v4, v4, v5
	v_mov_b32_e32 v5, v223
	v_mul_f32_e32 v6, 0x3fb8aa3b, v4
	v_exp_f32_e32 v6, v6
	s_waitcnt lgkmcnt(0)
	v_lshlrev_b32_e32 v5, 16, v5
	v_mul_f32_e32 v5, v6, v5
	v_cvt_pk_bf16_f32 v5, v5, s0
	ds_write_b16 v2, v5
	v_mul_f32_e32 v5, 0xbfb8aa3b, v4
	v_exp_f32_e32 v5, v5
	s_nop 0
	v_mul_f32_e32 v3, v3, v5
	v_cvt_pk_bf16_f32 v3, v3, s0
	ds_write_b16 v2, v3 offset:34816
	v_mov_b32_e32 v2, s10
	v_mov_b32_e32 v3, s11
	v_cndmask_b32_e64 v2, v2, v3, s[6:7]
	v_mad_u64_u32 v[2:3], s[10:11], v2, s77, v[86:87]
	v_mov_b32_e32 v3, v222
	s_waitcnt lgkmcnt(0)
	v_lshlrev_b32_e32 v3, 16, v3
	v_mul_f32_e32 v3, 0xbfb8aa3b, v3
	v_exp_f32_e32 v3, v3
	s_nop 0
	v_add_f32_e32 v3, 1.0, v3
	v_div_scale_f32 v5, s[10:11], v3, v3, 1.0
	v_rcp_f32_e32 v6, v5
	s_add_i32 s10, s68, 3
	s_add_i32 s11, s61, 4
	v_fma_f32 v7, -v5, v6, 1.0
	v_fmac_f32_e32 v6, v7, v6
	v_div_scale_f32 v7, vcc, 1.0, v3, 1.0
	v_mul_f32_e32 v8, v7, v6
	v_fma_f32 v9, -v5, v8, v7
	v_fmac_f32_e32 v8, v9, v6
	v_fma_f32 v5, -v5, v8, v7
	v_div_fmas_f32 v5, v5, v6, v8
	v_div_fixup_f32 v3, v5, v3, 1.0
	v_fma_f32 v3, v1, v3, v0
	v_cmp_gt_f32_e32 vcc, s95, v3
	s_nop 1
	v_cndmask_b32_e64 v5, 0, 32, vcc
	v_ldexp_f32 v5, v3, v5
	v_log_f32_e32 v5, v5
	v_sub_f32_e32 v3, 1.0, v3
	v_mul_f32_e32 v6, 0x3f317217, v5
	v_fma_f32 v6, v5, s96, -v6
	v_fmac_f32_e32 v6, 0x3377d1cf, v5
	v_fmac_f32_e32 v6, 0x3f317217, v5
	v_cmp_lt_f32_e64 s[42:43], |v5|, s97
	s_nop 1
	v_cndmask_b32_e64 v5, v5, v6, s[42:43]
	v_cndmask_b32_e32 v6, 0, v209, vcc
	v_sub_f32_e32 v5, v5, v6
	v_add_f32_e32 v4, v4, v5
	v_mov_b32_e32 v5, v221
	v_mul_f32_e32 v6, 0x3fb8aa3b, v4
	v_exp_f32_e32 v6, v6
	s_waitcnt lgkmcnt(0)
	v_lshlrev_b32_e32 v5, 16, v5
	v_mul_f32_e32 v5, v6, v5
	v_cvt_pk_bf16_f32 v5, v5, s0
	ds_write_b16 v2, v5
	v_mul_f32_e32 v5, 0xbfb8aa3b, v4
	v_exp_f32_e32 v5, v5
	s_nop 0
	v_mul_f32_e32 v3, v3, v5
	v_cvt_pk_bf16_f32 v3, v3, s0
	ds_write_b16 v2, v3 offset:34816
	v_mov_b32_e32 v2, s10
	v_mov_b32_e32 v3, s11
	v_cndmask_b32_e64 v2, v2, v3, s[6:7]
	v_mad_u64_u32 v[2:3], s[10:11], v2, s77, v[86:87]
	v_mov_b32_e32 v3, v220
	s_waitcnt lgkmcnt(0)
	v_lshlrev_b32_e32 v3, 16, v3
	v_mul_f32_e32 v3, 0xbfb8aa3b, v3
	v_exp_f32_e32 v3, v3
	s_nop 0
	v_add_f32_e32 v3, 1.0, v3
	v_div_scale_f32 v5, s[10:11], v3, v3, 1.0
	v_rcp_f32_e32 v6, v5
	s_add_i32 s10, s68, 2
	s_add_i32 s11, s61, 5
	v_fma_f32 v7, -v5, v6, 1.0
	v_fmac_f32_e32 v6, v7, v6
	v_div_scale_f32 v7, vcc, 1.0, v3, 1.0
	v_mul_f32_e32 v8, v7, v6
	v_fma_f32 v9, -v5, v8, v7
	v_fmac_f32_e32 v8, v9, v6
	v_fma_f32 v5, -v5, v8, v7
	v_div_fmas_f32 v5, v5, v6, v8
	v_div_fixup_f32 v3, v5, v3, 1.0
	v_fma_f32 v3, v1, v3, v0
	v_cmp_gt_f32_e32 vcc, s95, v3
	s_nop 1
	v_cndmask_b32_e64 v5, 0, 32, vcc
	v_ldexp_f32 v5, v3, v5
	v_log_f32_e32 v5, v5
	v_sub_f32_e32 v3, 1.0, v3
	v_mul_f32_e32 v6, 0x3f317217, v5
	v_fma_f32 v6, v5, s96, -v6
	v_fmac_f32_e32 v6, 0x3377d1cf, v5
	v_fmac_f32_e32 v6, 0x3f317217, v5
	v_cmp_lt_f32_e64 s[42:43], |v5|, s97
	s_nop 1
	v_cndmask_b32_e64 v5, v5, v6, s[42:43]
	v_cndmask_b32_e32 v6, 0, v209, vcc
	v_sub_f32_e32 v5, v5, v6
	v_add_f32_e32 v4, v4, v5
	v_mov_b32_e32 v5, v219
	v_mul_f32_e32 v6, 0x3fb8aa3b, v4
	v_exp_f32_e32 v6, v6
	s_waitcnt lgkmcnt(0)
	v_lshlrev_b32_e32 v5, 16, v5
	v_mul_f32_e32 v5, v6, v5
	v_cvt_pk_bf16_f32 v5, v5, s0
	ds_write_b16 v2, v5
	v_mul_f32_e32 v5, 0xbfb8aa3b, v4
	v_exp_f32_e32 v5, v5
	s_nop 0
	v_mul_f32_e32 v3, v3, v5
	v_cvt_pk_bf16_f32 v3, v3, s0
	ds_write_b16 v2, v3 offset:34816
	v_mov_b32_e32 v2, s10
	v_mov_b32_e32 v3, s11
	v_cndmask_b32_e64 v2, v2, v3, s[6:7]
	v_mad_u64_u32 v[2:3], s[10:11], v2, s77, v[86:87]
	v_mov_b32_e32 v3, v218
	s_waitcnt lgkmcnt(0)
; DEVI float bf2f(u16 h) { return __uint_as_float(((unsigned)h) << 16); }
; DEVI float sigm(float x) { return 1.f / (1.f + __expf(-x)); }
; DEVI void hgrn_c_item(int TID_, int BID_, PREF p, int item, char* shm) {
;     ...
;     float run = 0.f;
; #pragma unroll 8
;     for (int s = 0; s < 64; ++s) {
;       const int i = dir == 0 ? s : 63 - s;
;       float f = lbv + (1.f - lbv) * sigm(bf2f(kc[i * 136]));
;       run += __logf(f);
;       qc[i * 136] = f2bf(bf2f(qc[i * 136]) * __expf(run));
;       kc[i * 136] = f2bf((1.f - f) * __expf(-run));
;     }
	v_lshlrev_b32_e32 v3, 16, v3
	v_mul_f32_e32 v3, 0xbfb8aa3b, v3
	v_exp_f32_e32 v3, v3
	s_nop 0
	v_add_f32_e32 v3, 1.0, v3
	v_div_scale_f32 v5, s[10:11], v3, v3, 1.0
	v_rcp_f32_e32 v6, v5
	s_add_i32 s10, s68, 1
	s_add_i32 s11, s61, 6
	v_fma_f32 v7, -v5, v6, 1.0
	v_fmac_f32_e32 v6, v7, v6
	v_div_scale_f32 v7, vcc, 1.0, v3, 1.0
	v_mul_f32_e32 v8, v7, v6
	v_fma_f32 v9, -v5, v8, v7
	v_fmac_f32_e32 v8, v9, v6
	v_fma_f32 v5, -v5, v8, v7
	v_div_fmas_f32 v5, v5, v6, v8
	v_div_fixup_f32 v3, v5, v3, 1.0
	v_fma_f32 v3, v1, v3, v0
	v_cmp_gt_f32_e32 vcc, s95, v3
	s_nop 1
	v_cndmask_b32_e64 v5, 0, 32, vcc
	v_ldexp_f32 v5, v3, v5
	v_log_f32_e32 v5, v5
	v_sub_f32_e32 v3, 1.0, v3
	v_mul_f32_e32 v6, 0x3f317217, v5
	v_fma_f32 v6, v5, s96, -v6
	v_fmac_f32_e32 v6, 0x3377d1cf, v5
	v_fmac_f32_e32 v6, 0x3f317217, v5
	v_cmp_lt_f32_e64 s[42:43], |v5|, s97
	s_nop 1
	v_cndmask_b32_e64 v5, v5, v6, s[42:43]
	v_cndmask_b32_e32 v6, 0, v209, vcc
	v_sub_f32_e32 v5, v5, v6
	v_add_f32_e32 v4, v4, v5
	v_mov_b32_e32 v5, v217
	v_mul_f32_e32 v6, 0x3fb8aa3b, v4
	v_exp_f32_e32 v6, v6
	s_waitcnt lgkmcnt(0)
	v_lshlrev_b32_e32 v5, 16, v5
	v_mul_f32_e32 v5, v6, v5
	v_cvt_pk_bf16_f32 v5, v5, s0
	ds_write_b16 v2, v5
	v_mul_f32_e32 v5, 0xbfb8aa3b, v4
	v_exp_f32_e32 v5, v5
	s_nop 0
	v_mul_f32_e32 v3, v3, v5
	v_cvt_pk_bf16_f32 v3, v3, s0
	ds_write_b16 v2, v3 offset:34816
	v_mov_b32_e32 v2, s10
	v_mov_b32_e32 v3, s11
	v_cndmask_b32_e64 v2, v2, v3, s[6:7]
	v_mad_u64_u32 v[2:3], s[10:11], v2, s77, v[86:87]
	v_mov_b32_e32 v3, v216
	s_waitcnt lgkmcnt(0)
	v_lshlrev_b32_e32 v3, 16, v3
	v_mul_f32_e32 v3, 0xbfb8aa3b, v3
	v_exp_f32_e32 v3, v3
	s_nop 0
	v_add_f32_e32 v3, 1.0, v3
	v_div_scale_f32 v5, s[10:11], v3, v3, 1.0
	v_rcp_f32_e32 v6, v5
	s_add_i32 s10, s61, 7
	s_add_i32 s61, s61, 8
	v_fma_f32 v7, -v5, v6, 1.0
	v_fmac_f32_e32 v6, v7, v6
	v_div_scale_f32 v7, vcc, 1.0, v3, 1.0
	v_mul_f32_e32 v8, v7, v6
	v_fma_f32 v9, -v5, v8, v7
	v_fmac_f32_e32 v8, v9, v6
	v_fma_f32 v5, -v5, v8, v7
	v_div_fmas_f32 v5, v5, v6, v8
	v_div_fixup_f32 v3, v5, v3, 1.0
	v_fma_f32 v3, v1, v3, v0
	v_cmp_gt_f32_e32 vcc, s95, v3
	s_nop 1
	v_cndmask_b32_e64 v5, 0, 32, vcc
	v_ldexp_f32 v5, v3, v5
	v_log_f32_e32 v5, v5
	v_sub_f32_e32 v3, 1.0, v3
	v_mul_f32_e32 v6, 0x3f317217, v5
	v_fma_f32 v6, v5, s96, -v6
	v_fmac_f32_e32 v6, 0x3377d1cf, v5
	v_fmac_f32_e32 v6, 0x3f317217, v5
	v_cmp_lt_f32_e64 s[42:43], |v5|, s97
	s_nop 1
	v_cndmask_b32_e64 v5, v5, v6, s[42:43]
	v_cndmask_b32_e32 v6, 0, v209, vcc
	v_sub_f32_e32 v5, v5, v6
	v_add_f32_e32 v6, v4, v5
	v_mov_b32_e32 v4, v215
	v_mul_f32_e32 v5, 0x3fb8aa3b, v6
	v_exp_f32_e32 v5, v5
	s_waitcnt lgkmcnt(0)
	v_lshlrev_b32_e32 v4, 16, v4
	v_mul_f32_e32 v4, v5, v4
	v_cvt_pk_bf16_f32 v4, v4, s0
	ds_write_b16 v2, v4
	v_mul_f32_e32 v4, 0xbfb8aa3b, v6
	v_exp_f32_e32 v4, v4
	s_nop 0
	v_mul_f32_e32 v3, v3, v4
	v_cvt_pk_bf16_f32 v3, v3, s0
	ds_write_b16 v2, v3 offset:34816
	v_mov_b32_e32 v2, s68
	v_mov_b32_e32 v3, s10
	v_cndmask_b32_e64 v2, v2, v3, s[6:7]
	v_mad_u64_u32 v[4:5], s[10:11], v2, s77, v[86:87]
	v_mov_b32_e32 v2, v214
	s_add_i32 s68, s68, -8
	s_cmp_lg_u32 s61, 64
	s_waitcnt lgkmcnt(0)
	v_lshlrev_b32_e32 v2, 16, v2
	v_mul_f32_e32 v2, 0xbfb8aa3b, v2
	v_exp_f32_e32 v2, v2
	s_nop 0
	v_add_f32_e32 v2, 1.0, v2
	v_div_scale_f32 v3, s[10:11], v2, v2, 1.0
	v_rcp_f32_e32 v5, v3
	s_nop 0
	v_fma_f32 v7, -v3, v5, 1.0
	v_fmac_f32_e32 v5, v7, v5
	v_div_scale_f32 v7, vcc, 1.0, v2, 1.0
	v_mul_f32_e32 v8, v7, v5
	v_fma_f32 v9, -v3, v8, v7
	v_fmac_f32_e32 v8, v9, v5
	v_fma_f32 v3, -v3, v8, v7
	v_div_fmas_f32 v3, v3, v5, v8
	v_div_fixup_f32 v2, v3, v2, 1.0
	v_fma_f32 v3, v1, v2, v0
	v_cmp_gt_f32_e32 vcc, s95, v3
	s_nop 1
	v_cndmask_b32_e64 v2, 0, 32, vcc
	v_ldexp_f32 v2, v3, v2
	v_log_f32_e32 v2, v2
	v_sub_f32_e32 v3, 1.0, v3
	v_mul_f32_e32 v5, 0x3f317217, v2
	v_fma_f32 v5, v2, s96, -v5
	v_fmac_f32_e32 v5, 0x3377d1cf, v2
	v_fmac_f32_e32 v5, 0x3f317217, v2
	v_cmp_lt_f32_e64 s[42:43], |v2|, s97
	s_nop 1
	v_cndmask_b32_e64 v2, v2, v5, s[42:43]
	v_cndmask_b32_e32 v5, 0, v209, vcc
	v_sub_f32_e32 v2, v2, v5
	v_add_f32_e32 v2, v6, v2
	v_mov_b32_e32 v5, v213
	v_mul_f32_e32 v6, 0x3fb8aa3b, v2
	v_exp_f32_e32 v6, v6
	s_waitcnt lgkmcnt(0)
	v_lshlrev_b32_e32 v5, 16, v5
	v_mul_f32_e32 v5, v6, v5
	v_cvt_pk_bf16_f32 v5, v5, s0
	ds_write_b16 v4, v5
	v_mul_f32_e32 v5, 0xbfb8aa3b, v2
	v_exp_f32_e32 v5, v5
	s_nop 0
	v_mul_f32_e32 v3, v3, v5
	v_cvt_pk_bf16_f32 v3, v3, s0
	ds_write_b16 v4, v3 offset:34816
	s_cbranch_scc1 .LBB0_107

; DEVI float bf2f(u16 h) { return __uint_as_float(((unsigned)h) << 16); }
; DEVI float sigm(float x) { return 1.f / (1.f + __expf(-x)); }
; DEVI void hgrn_a_item(int TID_, int BID_, PREF p, int item, char* shm) {
;     ...
;     float run = 0.f;
; #pragma unroll 8
;     for (int s = 0; s < 64; ++s) {
;       const int j = dir == 0 ? 63 - s : s;
;       float f = lbv + (1.f - lbv) * sigm(bf2f(zc[j * 136]));
;       dst[j] = f2bf((1.f - f) * __expf(run));
;       run += __logf(f);
;     }
;     dec[((size_t)(c * 8 + h) * 2 + dir) * 128 + d] = __expf(run);
.LBB0_148:
	s_add_i32 s8, s22, 7
	s_add_i32 s9, s19, 0
	v_mov_b32_e32 v179, s9
	v_mov_b32_e32 v178, s8
	v_cndmask_b32_e64 v179, v179, v178, s[6:7]
	v_mad_u32_u24 v177, v179, s77, v12
	ds_read_u16 v169, v177 offset:55296
	s_add_i32 s8, s22, 6
	s_add_i32 s9, s19, 1
	v_mov_b32_e32 v179, s9
	v_mov_b32_e32 v178, s8
	v_cndmask_b32_e64 v179, v179, v178, s[6:7]
	v_mad_u32_u24 v176, v179, s77, v12
	ds_read_u16 v168, v176 offset:55296
	s_add_i32 s8, s22, 5
	s_add_i32 s9, s19, 2
	v_mov_b32_e32 v179, s9
	v_mov_b32_e32 v178, s8
	v_cndmask_b32_e64 v179, v179, v178, s[6:7]
	v_mad_u32_u24 v175, v179, s77, v12
	ds_read_u16 v167, v175 offset:55296
	s_add_i32 s8, s22, 4
	s_add_i32 s9, s19, 3
	v_mov_b32_e32 v179, s9
	v_mov_b32_e32 v178, s8
	v_cndmask_b32_e64 v179, v179, v178, s[6:7]
	v_mad_u32_u24 v174, v179, s77, v12
	ds_read_u16 v166, v174 offset:55296
	s_add_i32 s8, s22, 3
	s_add_i32 s9, s19, 4
	v_mov_b32_e32 v179, s9
	v_mov_b32_e32 v178, s8
	v_cndmask_b32_e64 v179, v179, v178, s[6:7]
	v_mad_u32_u24 v173, v179, s77, v12
	ds_read_u16 v165, v173 offset:55296
	s_add_i32 s8, s22, 2
	s_add_i32 s9, s19, 5
	v_mov_b32_e32 v179, s9
	v_mov_b32_e32 v178, s8
	v_cndmask_b32_e64 v179, v179, v178, s[6:7]
	v_mad_u32_u24 v172, v179, s77, v12
	ds_read_u16 v164, v172 offset:55296
	s_add_i32 s8, s22, 1
	s_add_i32 s9, s19, 6
	v_mov_b32_e32 v179, s9
	v_mov_b32_e32 v178, s8
	v_cndmask_b32_e64 v179, v179, v178, s[6:7]
	v_mad_u32_u24 v171, v179, s77, v12
	ds_read_u16 v163, v171 offset:55296
	s_add_i32 s8, s22, 0
	s_add_i32 s9, s19, 7
	v_mov_b32_e32 v179, s9
	v_mov_b32_e32 v178, s8
	v_cndmask_b32_e64 v179, v179, v178, s[6:7]
	v_mad_u32_u24 v170, v179, s77, v12
	ds_read_u16 v162, v170 offset:55296
	s_waitcnt lgkmcnt(0)
	s_add_i32 s8, s22, 7
	v_mov_b32_e32 v3, s19
	v_mov_b32_e32 v4, s8
	v_cndmask_b32_e64 v3, v3, v4, s[6:7]
	v_mad_u64_u32 v[4:5], s[8:9], v3, s77, v[12:13]
	v_mov_b32_e32 v4, v169
	v_lshl_add_u32 v3, v3, 1, v49
	s_waitcnt lgkmcnt(0)
	v_lshlrev_b32_e32 v4, 16, v4
	v_mul_f32_e32 v4, 0xbfb8aa3b, v4
	v_exp_f32_e32 v4, v4
	s_nop 0
	v_add_f32_e32 v4, 1.0, v4
	v_div_scale_f32 v5, s[8:9], v4, v4, 1.0
	v_rcp_f32_e32 v6, v5
	s_nop 0
	v_fma_f32 v7, -v5, v6, 1.0
	v_fmac_f32_e32 v6, v7, v6
	v_div_scale_f32 v7, vcc, 1.0, v4, 1.0
	v_mul_f32_e32 v19, v7, v6
	v_fma_f32 v38, -v5, v19, v7
	v_fmac_f32_e32 v19, v38, v6
	v_fma_f32 v5, -v5, v19, v7
	v_div_fmas_f32 v5, v5, v6, v19
	v_mul_f32_e32 v6, 0x3fb8aa3b, v2
	v_exp_f32_e32 v6, v6
	v_div_fixup_f32 v4, v5, v4, 1.0
	v_fma_f32 v4, v1, v4, v0
	v_sub_f32_e32 v5, 1.0, v4
	v_mul_f32_e32 v5, v6, v5
	v_cvt_pk_bf16_f32 v5, v5, s0
	v_cmp_gt_f32_e32 vcc, s95, v4
	ds_write_b16 v3, v5 offset:18432
	s_nop 0
	v_cndmask_b32_e64 v3, 0, 32, vcc
	v_ldexp_f32 v3, v4, v3
	v_log_f32_e32 v3, v3
	s_nop 0
	v_mul_f32_e32 v4, 0x3f317217, v3
	v_fma_f32 v4, v3, s96, -v4
	v_fmac_f32_e32 v4, 0x3377d1cf, v3
	v_fmac_f32_e32 v4, 0x3f317217, v3
	v_cmp_lt_f32_e64 s[8:9], |v3|, s97
	s_nop 1
	v_cndmask_b32_e64 v3, v3, v4, s[8:9]
	v_cndmask_b32_e32 v4, 0, v209, vcc
	v_sub_f32_e32 v3, v3, v4
	s_add_i32 s8, s22, 6
	s_add_i32 s9, s19, 1
	v_add_f32_e32 v4, v2, v3
	v_mov_b32_e32 v2, s9
	v_mov_b32_e32 v3, s8
	v_cndmask_b32_e64 v5, v2, v3, s[6:7]
	v_mad_u64_u32 v[2:3], s[8:9], v5, s77, v[12:13]
	v_mov_b32_e32 v2, v168
	v_lshl_add_u32 v5, v5, 1, v49
	s_waitcnt lgkmcnt(0)
	v_lshlrev_b32_e32 v2, 16, v2
	v_mul_f32_e32 v2, 0xbfb8aa3b, v2
	v_exp_f32_e32 v2, v2
	s_nop 0
	v_add_f32_e32 v2, 1.0, v2
	v_div_scale_f32 v3, s[8:9], v2, v2, 1.0
	v_rcp_f32_e32 v6, v3
	s_nop 0
	v_fma_f32 v7, -v3, v6, 1.0
	v_fmac_f32_e32 v6, v7, v6
	v_div_scale_f32 v7, vcc, 1.0, v2, 1.0
	v_mul_f32_e32 v19, v7, v6
	v_fma_f32 v38, -v3, v19, v7
	v_fmac_f32_e32 v19, v38, v6
	v_fma_f32 v3, -v3, v19, v7
	v_div_fmas_f32 v3, v3, v6, v19
	v_mul_f32_e32 v6, 0x3fb8aa3b, v4
	v_exp_f32_e32 v6, v6
	v_div_fixup_f32 v2, v3, v2, 1.0
	v_fma_f32 v2, v1, v2, v0
	v_sub_f32_e32 v3, 1.0, v2
	v_mul_f32_e32 v3, v6, v3
	v_cvt_pk_bf16_f32 v3, v3, s0
	v_cmp_gt_f32_e32 vcc, s95, v2
	ds_write_b16 v5, v3 offset:18432
	s_nop 0
	v_cndmask_b32_e64 v3, 0, 32, vcc
	v_ldexp_f32 v2, v2, v3
	v_log_f32_e32 v2, v2
	s_nop 0
	v_mul_f32_e32 v3, 0x3f317217, v2
	v_fma_f32 v3, v2, s96, -v3
	v_fmac_f32_e32 v3, 0x3377d1cf, v2
	v_fmac_f32_e32 v3, 0x3f317217, v2
	v_cmp_lt_f32_e64 s[8:9], |v2|, s97
	s_nop 1
	v_cndmask_b32_e64 v2, v2, v3, s[8:9]
	v_cndmask_b32_e32 v3, 0, v209, vcc
	v_sub_f32_e32 v2, v2, v3
	s_add_i32 s8, s22, 5
	s_add_i32 s9, s19, 2
	v_add_f32_e32 v4, v4, v2
	v_mov_b32_e32 v2, s9
	v_mov_b32_e32 v3, s8
	v_cndmask_b32_e64 v5, v2, v3, s[6:7]
	v_mad_u64_u32 v[2:3], s[8:9], v5, s77, v[12:13]
	v_mov_b32_e32 v2, v167
	v_lshl_add_u32 v5, v5, 1, v49
	s_waitcnt lgkmcnt(0)
	v_lshlrev_b32_e32 v2, 16, v2
	v_mul_f32_e32 v2, 0xbfb8aa3b, v2
	v_exp_f32_e32 v2, v2
	s_nop 0
	v_add_f32_e32 v2, 1.0, v2
	v_div_scale_f32 v3, s[8:9], v2, v2, 1.0
	v_rcp_f32_e32 v6, v3
	s_nop 0
	v_fma_f32 v7, -v3, v6, 1.0
	v_fmac_f32_e32 v6, v7, v6
	v_div_scale_f32 v7, vcc, 1.0, v2, 1.0
	v_mul_f32_e32 v19, v7, v6
	v_fma_f32 v38, -v3, v19, v7
	v_fmac_f32_e32 v19, v38, v6
	v_fma_f32 v3, -v3, v19, v7
	v_div_fmas_f32 v3, v3, v6, v19
	v_mul_f32_e32 v6, 0x3fb8aa3b, v4
	v_exp_f32_e32 v6, v6
	v_div_fixup_f32 v2, v3, v2, 1.0
	v_fma_f32 v2, v1, v2, v0
	v_sub_f32_e32 v3, 1.0, v2
	v_mul_f32_e32 v3, v6, v3
	v_cvt_pk_bf16_f32 v3, v3, s0
	v_cmp_gt_f32_e32 vcc, s95, v2
	ds_write_b16 v5, v3 offset:18432
	s_nop 0
	v_cndmask_b32_e64 v3, 0, 32, vcc
	v_ldexp_f32 v2, v2, v3
	v_log_f32_e32 v2, v2
	s_nop 0
	v_mul_f32_e32 v3, 0x3f317217, v2
	v_fma_f32 v3, v2, s96, -v3
	v_fmac_f32_e32 v3, 0x3377d1cf, v2
	v_fmac_f32_e32 v3, 0x3f317217, v2
	v_cmp_lt_f32_e64 s[8:9], |v2|, s97
	s_nop 1
	v_cndmask_b32_e64 v2, v2, v3, s[8:9]
	v_cndmask_b32_e32 v3, 0, v209, vcc
	v_sub_f32_e32 v2, v2, v3
	s_add_i32 s8, s22, 4
	s_add_i32 s9, s19, 3
	v_add_f32_e32 v4, v4, v2
	v_mov_b32_e32 v2, s9
	v_mov_b32_e32 v3, s8
	v_cndmask_b32_e64 v5, v2, v3, s[6:7]
	v_mad_u64_u32 v[2:3], s[8:9], v5, s77, v[12:13]
	v_mov_b32_e32 v2, v166
	v_lshl_add_u32 v5, v5, 1, v49
	s_waitcnt lgkmcnt(0)
; DEVI float bf2f(u16 h) { return __uint_as_float(((unsigned)h) << 16); }
; DEVI float sigm(float x) { return 1.f / (1.f + __expf(-x)); }
; DEVI void hgrn_a_item(int TID_, int BID_, PREF p, int item, char* shm) {
;     ...
;     float run = 0.f;
; #pragma unroll 8
;     for (int s = 0; s < 64; ++s) {
;       const int j = dir == 0 ? 63 - s : s;
;       float f = lbv + (1.f - lbv) * sigm(bf2f(zc[j * 136]));
;       dst[j] = f2bf((1.f - f) * __expf(run));
;       run += __logf(f);
;     }
;     dec[((size_t)(c * 8 + h) * 2 + dir) * 128 + d] = __expf(run);
	v_lshlrev_b32_e32 v2, 16, v2
	v_mul_f32_e32 v2, 0xbfb8aa3b, v2
	v_exp_f32_e32 v2, v2
	s_nop 0
	v_add_f32_e32 v2, 1.0, v2
	v_div_scale_f32 v3, s[8:9], v2, v2, 1.0
	v_rcp_f32_e32 v6, v3
	s_nop 0
	v_fma_f32 v7, -v3, v6, 1.0
	v_fmac_f32_e32 v6, v7, v6
	v_div_scale_f32 v7, vcc, 1.0, v2, 1.0
	v_mul_f32_e32 v19, v7, v6
	v_fma_f32 v38, -v3, v19, v7
	v_fmac_f32_e32 v19, v38, v6
	v_fma_f32 v3, -v3, v19, v7
	v_div_fmas_f32 v3, v3, v6, v19
	v_mul_f32_e32 v6, 0x3fb8aa3b, v4
	v_exp_f32_e32 v6, v6
	v_div_fixup_f32 v2, v3, v2, 1.0
	v_fma_f32 v2, v1, v2, v0
	v_sub_f32_e32 v3, 1.0, v2
	v_mul_f32_e32 v3, v6, v3
	v_cvt_pk_bf16_f32 v3, v3, s0
	v_cmp_gt_f32_e32 vcc, s95, v2
	ds_write_b16 v5, v3 offset:18432
	s_nop 0
	v_cndmask_b32_e64 v3, 0, 32, vcc
	v_ldexp_f32 v2, v2, v3
	v_log_f32_e32 v2, v2
	s_nop 0
	v_mul_f32_e32 v3, 0x3f317217, v2
	v_fma_f32 v3, v2, s96, -v3
	v_fmac_f32_e32 v3, 0x3377d1cf, v2
	v_fmac_f32_e32 v3, 0x3f317217, v2
	v_cmp_lt_f32_e64 s[8:9], |v2|, s97
	s_nop 1
	v_cndmask_b32_e64 v2, v2, v3, s[8:9]
	v_cndmask_b32_e32 v3, 0, v209, vcc
	v_sub_f32_e32 v2, v2, v3
	s_add_i32 s8, s22, 3
	s_add_i32 s9, s19, 4
	v_add_f32_e32 v4, v4, v2
	v_mov_b32_e32 v2, s9
	v_mov_b32_e32 v3, s8
	v_cndmask_b32_e64 v5, v2, v3, s[6:7]
	v_mad_u64_u32 v[2:3], s[8:9], v5, s77, v[12:13]
	v_mov_b32_e32 v2, v165
	v_lshl_add_u32 v5, v5, 1, v49
	s_waitcnt lgkmcnt(0)
	v_lshlrev_b32_e32 v2, 16, v2
	v_mul_f32_e32 v2, 0xbfb8aa3b, v2
	v_exp_f32_e32 v2, v2
	s_nop 0
	v_add_f32_e32 v2, 1.0, v2
	v_div_scale_f32 v3, s[8:9], v2, v2, 1.0
	v_rcp_f32_e32 v6, v3
	s_nop 0
	v_fma_f32 v7, -v3, v6, 1.0
	v_fmac_f32_e32 v6, v7, v6
	v_div_scale_f32 v7, vcc, 1.0, v2, 1.0
	v_mul_f32_e32 v19, v7, v6
	v_fma_f32 v38, -v3, v19, v7
	v_fmac_f32_e32 v19, v38, v6
	v_fma_f32 v3, -v3, v19, v7
	v_div_fmas_f32 v3, v3, v6, v19
	v_mul_f32_e32 v6, 0x3fb8aa3b, v4
	v_exp_f32_e32 v6, v6
	v_div_fixup_f32 v2, v3, v2, 1.0
	v_fma_f32 v2, v1, v2, v0
	v_sub_f32_e32 v3, 1.0, v2
	v_mul_f32_e32 v3, v6, v3
	v_cvt_pk_bf16_f32 v3, v3, s0
	v_cmp_gt_f32_e32 vcc, s95, v2
	ds_write_b16 v5, v3 offset:18432
	s_nop 0
	v_cndmask_b32_e64 v3, 0, 32, vcc
	v_ldexp_f32 v2, v2, v3
	v_log_f32_e32 v2, v2
	s_nop 0
	v_mul_f32_e32 v3, 0x3f317217, v2
	v_fma_f32 v3, v2, s96, -v3
	v_fmac_f32_e32 v3, 0x3377d1cf, v2
	v_fmac_f32_e32 v3, 0x3f317217, v2
	v_cmp_lt_f32_e64 s[8:9], |v2|, s97
	s_nop 1
	v_cndmask_b32_e64 v2, v2, v3, s[8:9]
	v_cndmask_b32_e32 v3, 0, v209, vcc
	v_sub_f32_e32 v2, v2, v3
	s_add_i32 s8, s22, 2
	s_add_i32 s9, s19, 5
	v_add_f32_e32 v4, v4, v2
	v_mov_b32_e32 v2, s9
	v_mov_b32_e32 v3, s8
	v_cndmask_b32_e64 v5, v2, v3, s[6:7]
	v_mad_u64_u32 v[2:3], s[8:9], v5, s77, v[12:13]
	v_mov_b32_e32 v2, v164
	v_lshl_add_u32 v5, v5, 1, v49
	s_waitcnt lgkmcnt(0)
	v_lshlrev_b32_e32 v2, 16, v2
	v_mul_f32_e32 v2, 0xbfb8aa3b, v2
	v_exp_f32_e32 v2, v2
	s_nop 0
	v_add_f32_e32 v2, 1.0, v2
	v_div_scale_f32 v3, s[8:9], v2, v2, 1.0
	v_rcp_f32_e32 v6, v3
	s_nop 0
	v_fma_f32 v7, -v3, v6, 1.0
	v_fmac_f32_e32 v6, v7, v6
	v_div_scale_f32 v7, vcc, 1.0, v2, 1.0
	v_mul_f32_e32 v19, v7, v6
	v_fma_f32 v38, -v3, v19, v7
	v_fmac_f32_e32 v19, v38, v6
	v_fma_f32 v3, -v3, v19, v7
	v_div_fmas_f32 v3, v3, v6, v19
	v_mul_f32_e32 v6, 0x3fb8aa3b, v4
	v_exp_f32_e32 v6, v6
	v_div_fixup_f32 v2, v3, v2, 1.0
	v_fma_f32 v2, v1, v2, v0
	v_sub_f32_e32 v3, 1.0, v2
	v_mul_f32_e32 v3, v6, v3
	v_cvt_pk_bf16_f32 v3, v3, s0
	v_cmp_gt_f32_e32 vcc, s95, v2
	ds_write_b16 v5, v3 offset:18432
	s_nop 0
	v_cndmask_b32_e64 v3, 0, 32, vcc
	v_ldexp_f32 v2, v2, v3
	v_log_f32_e32 v2, v2
	s_nop 0
	v_mul_f32_e32 v3, 0x3f317217, v2
	v_fma_f32 v3, v2, s96, -v3
	v_fmac_f32_e32 v3, 0x3377d1cf, v2
	v_fmac_f32_e32 v3, 0x3f317217, v2
	v_cmp_lt_f32_e64 s[8:9], |v2|, s97
	s_nop 1
	v_cndmask_b32_e64 v2, v2, v3, s[8:9]
	v_cndmask_b32_e32 v3, 0, v209, vcc
	v_sub_f32_e32 v2, v2, v3
	s_add_i32 s8, s22, 1
	s_add_i32 s9, s19, 6
	v_add_f32_e32 v4, v4, v2
	v_mov_b32_e32 v2, s9
	v_mov_b32_e32 v3, s8
	v_cndmask_b32_e64 v5, v2, v3, s[6:7]
	v_mad_u64_u32 v[2:3], s[8:9], v5, s77, v[12:13]
	v_mov_b32_e32 v2, v163
	v_lshl_add_u32 v5, v5, 1, v49
	s_waitcnt lgkmcnt(0)
	v_lshlrev_b32_e32 v2, 16, v2
	v_mul_f32_e32 v2, 0xbfb8aa3b, v2
	v_exp_f32_e32 v2, v2
	s_nop 0
	v_add_f32_e32 v2, 1.0, v2
	v_div_scale_f32 v3, s[8:9], v2, v2, 1.0
	v_rcp_f32_e32 v6, v3
	s_nop 0
	v_fma_f32 v7, -v3, v6, 1.0
	v_fmac_f32_e32 v6, v7, v6
	v_div_scale_f32 v7, vcc, 1.0, v2, 1.0
	v_mul_f32_e32 v19, v7, v6
	v_fma_f32 v38, -v3, v19, v7
	v_fmac_f32_e32 v19, v38, v6
	v_fma_f32 v3, -v3, v19, v7
	v_div_fmas_f32 v3, v3, v6, v19
	v_mul_f32_e32 v6, 0x3fb8aa3b, v4
	v_exp_f32_e32 v6, v6
	v_div_fixup_f32 v2, v3, v2, 1.0
	v_fma_f32 v2, v1, v2, v0
	v_sub_f32_e32 v3, 1.0, v2
	v_mul_f32_e32 v3, v6, v3
	v_cvt_pk_bf16_f32 v3, v3, s0
	v_cmp_gt_f32_e32 vcc, s95, v2
	ds_write_b16 v5, v3 offset:18432
	s_nop 0
	v_cndmask_b32_e64 v3, 0, 32, vcc
	v_ldexp_f32 v2, v2, v3
	v_log_f32_e32 v2, v2
	s_nop 0
	v_mul_f32_e32 v3, 0x3f317217, v2
	v_fma_f32 v3, v2, s96, -v3
	v_fmac_f32_e32 v3, 0x3377d1cf, v2
	v_fmac_f32_e32 v3, 0x3f317217, v2
	v_cmp_lt_f32_e64 s[8:9], |v2|, s97
	s_nop 1
	v_cndmask_b32_e64 v2, v2, v3, s[8:9]
	v_cndmask_b32_e32 v3, 0, v209, vcc
	v_sub_f32_e32 v2, v2, v3
	s_add_i32 s8, s19, 7
	v_add_f32_e32 v4, v4, v2
	v_mov_b32_e32 v2, s8
	v_mov_b32_e32 v3, s22
	v_cndmask_b32_e64 v5, v2, v3, s[6:7]
	v_mad_u64_u32 v[2:3], s[8:9], v5, s77, v[12:13]
	v_mov_b32_e32 v2, v162
	v_lshl_add_u32 v5, v5, 1, v49
	s_add_i32 s22, s22, -8
	s_add_i32 s19, s19, 8
	s_cmp_eq_u32 s19, 64
	s_waitcnt lgkmcnt(0)
	v_lshlrev_b32_e32 v2, 16, v2
	v_mul_f32_e32 v2, 0xbfb8aa3b, v2
	v_exp_f32_e32 v2, v2
	s_nop 0
	v_add_f32_e32 v2, 1.0, v2
	v_div_scale_f32 v3, s[8:9], v2, v2, 1.0
	v_rcp_f32_e32 v6, v3
	s_nop 0
	v_fma_f32 v7, -v3, v6, 1.0
	v_fmac_f32_e32 v6, v7, v6
	v_div_scale_f32 v7, vcc, 1.0, v2, 1.0
	v_mul_f32_e32 v19, v7, v6
	v_fma_f32 v38, -v3, v19, v7
	v_fmac_f32_e32 v19, v38, v6
	v_fma_f32 v3, -v3, v19, v7
	v_div_fmas_f32 v3, v3, v6, v19
	v_mul_f32_e32 v6, 0x3fb8aa3b, v4
	v_exp_f32_e32 v6, v6
	v_div_fixup_f32 v2, v3, v2, 1.0
	v_fma_f32 v2, v1, v2, v0
	v_sub_f32_e32 v3, 1.0, v2
	v_mul_f32_e32 v3, v6, v3
	v_cvt_pk_bf16_f32 v3, v3, s0
	v_cmp_gt_f32_e32 vcc, s95, v2
	ds_write_b16 v5, v3 offset:18432
	s_nop 0
	v_cndmask_b32_e64 v3, 0, 32, vcc
	v_ldexp_f32 v2, v2, v3
	v_log_f32_e32 v2, v2
	s_nop 0
	v_mul_f32_e32 v3, 0x3f317217, v2
	v_fma_f32 v3, v2, s96, -v3
	v_fmac_f32_e32 v3, 0x3377d1cf, v2
	v_fmac_f32_e32 v3, 0x3f317217, v2
	v_cmp_lt_f32_e64 s[8:9], |v2|, s97
	s_nop 1
	v_cndmask_b32_e64 v2, v2, v3, s[8:9]
	v_cndmask_b32_e32 v3, 0, v209, vcc
	v_sub_f32_e32 v2, v2, v3
	v_add_f32_e32 v2, v4, v2
	s_cbranch_scc0 .LBB0_148
	v_mul_f32_e32 v0, 0x3fb8aa3b, v2
	v_exp_f32_e32 v2, v0
	s_mov_b32 s19, s69
	s_lshl_b64 s[8:9], s[18:19], 10
	v_lshl_add_u64 v[0:1], v[14:15], 0, s[8:9]
	global_store_dword v[0:1], v2, off
	v_mov_b64_e32 v[0:1], s[18:19]

; DEVI float bf2f(u16 h) { return __uint_as_float(((unsigned)h) << 16); }
; DEVI float sigm(float x) { return 1.f / (1.f + __expf(-x)); }
; DEVI void hgrn_c_item(int TID_, int BID_, PREF p, int item, char* shm) {
;     ...
;     float run = 0.f;
; #pragma unroll 8
;     for (int s = 0; s < 64; ++s) {
;       const int i = dir == 0 ? s : 63 - s;
;       float f = lbv + (1.f - lbv) * sigm(bf2f(kc[i * 136]));
;       run += __logf(f);
;       qc[i * 136] = f2bf(bf2f(qc[i * 136]) * __expf(run));
;       kc[i * 136] = f2bf((1.f - f) * __expf(-run));
;     }
.LBB0_197:
	s_add_i32 s42, s55, 7
	s_add_i32 s43, s47, 0
	v_mov_b32_e32 v179, s42
	v_mov_b32_e32 v178, s43
	v_cndmask_b32_e64 v179, v179, v178, s[6:7]
	v_mad_u32_u24 v177, v179, s77, v56
	ds_read_u16 v169, v177 offset:34816
	ds_read_u16 v168, v177
	s_add_i32 s42, s55, 6
	s_add_i32 s43, s47, 1
	v_mov_b32_e32 v179, s42
	v_mov_b32_e32 v178, s43
	v_cndmask_b32_e64 v179, v179, v178, s[6:7]
	v_mad_u32_u24 v176, v179, s77, v56
	ds_read_u16 v167, v176 offset:34816
	ds_read_u16 v166, v176
	s_add_i32 s42, s55, 5
	s_add_i32 s43, s47, 2
	v_mov_b32_e32 v179, s42
	v_mov_b32_e32 v178, s43
	v_cndmask_b32_e64 v179, v179, v178, s[6:7]
	v_mad_u32_u24 v175, v179, s77, v56
	ds_read_u16 v165, v175 offset:34816
	ds_read_u16 v164, v175
	s_add_i32 s42, s55, 4
	s_add_i32 s43, s47, 3
	v_mov_b32_e32 v179, s42
	v_mov_b32_e32 v178, s43
	v_cndmask_b32_e64 v179, v179, v178, s[6:7]
	v_mad_u32_u24 v174, v179, s77, v56
	ds_read_u16 v163, v174 offset:34816
	ds_read_u16 v162, v174
	s_add_i32 s42, s55, 3
	s_add_i32 s43, s47, 4
	v_mov_b32_e32 v179, s42
	v_mov_b32_e32 v178, s43
	v_cndmask_b32_e64 v179, v179, v178, s[6:7]
	v_mad_u32_u24 v173, v179, s77, v56
	ds_read_u16 v161, v173 offset:34816
	ds_read_u16 v160, v173
	s_add_i32 s42, s55, 2
	s_add_i32 s43, s47, 5
	v_mov_b32_e32 v179, s42
	v_mov_b32_e32 v178, s43
	v_cndmask_b32_e64 v179, v179, v178, s[6:7]
	v_mad_u32_u24 v172, v179, s77, v56
	ds_read_u16 v159, v172 offset:34816
	ds_read_u16 v158, v172
	s_add_i32 s42, s55, 1
	s_add_i32 s43, s47, 6
	v_mov_b32_e32 v179, s42
	v_mov_b32_e32 v178, s43
	v_cndmask_b32_e64 v179, v179, v178, s[6:7]
	v_mad_u32_u24 v171, v179, s77, v56
	ds_read_u16 v157, v171 offset:34816
	ds_read_u16 v156, v171
	s_add_i32 s42, s55, 0
	s_add_i32 s43, s47, 7
	v_mov_b32_e32 v179, s42
	v_mov_b32_e32 v178, s43
	v_cndmask_b32_e64 v179, v179, v178, s[6:7]
	v_mad_u32_u24 v170, v179, s77, v56
	ds_read_u16 v155, v170 offset:34816
	ds_read_u16 v154, v170
	s_waitcnt lgkmcnt(0)
	s_add_i32 s42, s55, 7
	v_mov_b32_e32 v3, s42
	v_mov_b32_e32 v4, s47
	v_cndmask_b32_e64 v3, v3, v4, s[6:7]
	v_mad_u64_u32 v[4:5], s[42:43], v3, s77, v[56:57]
	v_mov_b32_e32 v3, v169
	s_waitcnt lgkmcnt(0)
	v_lshlrev_b32_e32 v3, 16, v3
	v_mul_f32_e32 v3, 0xbfb8aa3b, v3
	v_exp_f32_e32 v3, v3
	s_nop 0
	v_add_f32_e32 v3, 1.0, v3
	v_div_scale_f32 v5, s[42:43], v3, v3, 1.0
	v_rcp_f32_e32 v6, v5
	s_nop 0
	v_fma_f32 v7, -v5, v6, 1.0
	v_fmac_f32_e32 v6, v7, v6
	v_div_scale_f32 v7, vcc, 1.0, v3, 1.0
	v_mul_f32_e32 v8, v7, v6
	v_fma_f32 v9, -v5, v8, v7
	v_fmac_f32_e32 v8, v9, v6
	v_fma_f32 v5, -v5, v8, v7
	v_div_fmas_f32 v5, v5, v6, v8
	v_div_fixup_f32 v3, v5, v3, 1.0
	v_fma_f32 v3, v1, v3, v0
	v_cmp_gt_f32_e32 vcc, s95, v3
	s_nop 1
	v_cndmask_b32_e64 v5, 0, 32, vcc
	v_ldexp_f32 v5, v3, v5
	v_log_f32_e32 v5, v5
	s_nop 0
	v_mul_f32_e32 v6, 0x3f317217, v5
	v_fma_f32 v6, v5, s96, -v6
	v_fmac_f32_e32 v6, 0x3377d1cf, v5
	v_fmac_f32_e32 v6, 0x3f317217, v5
	v_cmp_lt_f32_e64 s[42:43], |v5|, s97
	s_nop 1
	v_cndmask_b32_e64 v5, v5, v6, s[42:43]
	v_cndmask_b32_e32 v6, 0, v209, vcc
	v_sub_f32_e32 v5, v5, v6
	v_add_f32_e32 v5, v2, v5
	v_mov_b32_e32 v2, v168
	v_mul_f32_e32 v6, 0x3fb8aa3b, v5
	v_exp_f32_e32 v6, v6
	s_add_i32 s42, s55, 6
	s_add_i32 s43, s47, 1
	s_waitcnt lgkmcnt(0)
	v_lshlrev_b32_e32 v2, 16, v2
	v_mul_f32_e32 v2, v6, v2
	v_cvt_pk_bf16_f32 v2, v2, s0
	ds_write_b16 v4, v2
	v_sub_f32_e32 v2, 1.0, v3
	v_mul_f32_e32 v3, 0xbfb8aa3b, v5
	v_exp_f32_e32 v3, v3
	s_nop 0
	v_mul_f32_e32 v2, v2, v3
	v_cvt_pk_bf16_f32 v2, v2, s0
	ds_write_b16 v4, v2 offset:34816
	v_mov_b32_e32 v2, s42
	v_mov_b32_e32 v3, s43
	v_cndmask_b32_e64 v2, v2, v3, s[6:7]
	v_mad_u64_u32 v[2:3], s[42:43], v2, s77, v[56:57]
	v_mov_b32_e32 v3, v167
	s_waitcnt lgkmcnt(0)
	v_lshlrev_b32_e32 v3, 16, v3
	v_mul_f32_e32 v3, 0xbfb8aa3b, v3
	v_exp_f32_e32 v3, v3
	s_nop 0
	v_add_f32_e32 v3, 1.0, v3
	v_div_scale_f32 v4, s[42:43], v3, v3, 1.0
	v_rcp_f32_e32 v6, v4
	s_nop 0
	v_fma_f32 v7, -v4, v6, 1.0
	v_fmac_f32_e32 v6, v7, v6
	v_div_scale_f32 v7, vcc, 1.0, v3, 1.0
	v_mul_f32_e32 v8, v7, v6
	v_fma_f32 v9, -v4, v8, v7
	v_fmac_f32_e32 v8, v9, v6
	v_fma_f32 v4, -v4, v8, v7
	v_div_fmas_f32 v4, v4, v6, v8
	v_div_fixup_f32 v3, v4, v3, 1.0
	v_fma_f32 v3, v1, v3, v0
	v_cmp_gt_f32_e32 vcc, s95, v3
	s_nop 1
	v_cndmask_b32_e64 v4, 0, 32, vcc
	v_ldexp_f32 v4, v3, v4
	v_log_f32_e32 v4, v4
	v_sub_f32_e32 v3, 1.0, v3
	v_mul_f32_e32 v6, 0x3f317217, v4
	v_fma_f32 v6, v4, s96, -v6
	v_fmac_f32_e32 v6, 0x3377d1cf, v4
	v_fmac_f32_e32 v6, 0x3f317217, v4
	v_cmp_lt_f32_e64 s[42:43], |v4|, s97
	s_nop 1
	v_cndmask_b32_e64 v4, v4, v6, s[42:43]
	v_cndmask_b32_e32 v6, 0, v209, vcc
	v_sub_f32_e32 v4, v4, v6
	v_add_f32_e32 v4, v5, v4
	v_mov_b32_e32 v5, v166
	v_mul_f32_e32 v6, 0x3fb8aa3b, v4
	v_exp_f32_e32 v6, v6
	s_add_i32 s42, s55, 5
	s_add_i32 s43, s47, 2
	s_waitcnt lgkmcnt(0)
	v_lshlrev_b32_e32 v5, 16, v5
	v_mul_f32_e32 v5, v6, v5
	v_cvt_pk_bf16_f32 v5, v5, s0
	ds_write_b16 v2, v5
	v_mul_f32_e32 v5, 0xbfb8aa3b, v4
	v_exp_f32_e32 v5, v5
	s_nop 0
	v_mul_f32_e32 v3, v3, v5
	v_cvt_pk_bf16_f32 v3, v3, s0
	ds_write_b16 v2, v3 offset:34816
	v_mov_b32_e32 v2, s42
	v_mov_b32_e32 v3, s43
	v_cndmask_b32_e64 v2, v2, v3, s[6:7]
	v_mad_u64_u32 v[2:3], s[42:43], v2, s77, v[56:57]
	v_mov_b32_e32 v3, v165
	s_waitcnt lgkmcnt(0)
; DEVI float bf2f(u16 h) { return __uint_as_float(((unsigned)h) << 16); }
; DEVI float sigm(float x) { return 1.f / (1.f + __expf(-x)); }
; DEVI void hgrn_c_item(int TID_, int BID_, PREF p, int item, char* shm) {
;     ...
;     float run = 0.f;
; #pragma unroll 8
;     for (int s = 0; s < 64; ++s) {
;       const int i = dir == 0 ? s : 63 - s;
;       float f = lbv + (1.f - lbv) * sigm(bf2f(kc[i * 136]));
;       run += __logf(f);
;       qc[i * 136] = f2bf(bf2f(qc[i * 136]) * __expf(run));
;       kc[i * 136] = f2bf((1.f - f) * __expf(-run));
;     }
	v_lshlrev_b32_e32 v3, 16, v3
	v_mul_f32_e32 v3, 0xbfb8aa3b, v3
	v_exp_f32_e32 v3, v3
	s_nop 0
	v_add_f32_e32 v3, 1.0, v3
	v_div_scale_f32 v5, s[42:43], v3, v3, 1.0
	v_rcp_f32_e32 v6, v5
	s_nop 0
	v_fma_f32 v7, -v5, v6, 1.0
	v_fmac_f32_e32 v6, v7, v6
	v_div_scale_f32 v7, vcc, 1.0, v3, 1.0
	v_mul_f32_e32 v8, v7, v6
	v_fma_f32 v9, -v5, v8, v7
	v_fmac_f32_e32 v8, v9, v6
	v_fma_f32 v5, -v5, v8, v7
	v_div_fmas_f32 v5, v5, v6, v8
	v_div_fixup_f32 v3, v5, v3, 1.0
	v_fma_f32 v3, v1, v3, v0
	v_cmp_gt_f32_e32 vcc, s95, v3
	s_nop 1
	v_cndmask_b32_e64 v5, 0, 32, vcc
	v_ldexp_f32 v5, v3, v5
	v_log_f32_e32 v5, v5
	v_sub_f32_e32 v3, 1.0, v3
	v_mul_f32_e32 v6, 0x3f317217, v5
	v_fma_f32 v6, v5, s96, -v6
	v_fmac_f32_e32 v6, 0x3377d1cf, v5
	v_fmac_f32_e32 v6, 0x3f317217, v5
	v_cmp_lt_f32_e64 s[42:43], |v5|, s97
	s_nop 1
	v_cndmask_b32_e64 v5, v5, v6, s[42:43]
	v_cndmask_b32_e32 v6, 0, v209, vcc
	v_sub_f32_e32 v5, v5, v6
	v_add_f32_e32 v4, v4, v5
	v_mov_b32_e32 v5, v164
	v_mul_f32_e32 v6, 0x3fb8aa3b, v4
	v_exp_f32_e32 v6, v6
	s_add_i32 s42, s55, 4
	s_add_i32 s43, s47, 3
	s_waitcnt lgkmcnt(0)
	v_lshlrev_b32_e32 v5, 16, v5
	v_mul_f32_e32 v5, v6, v5
	v_cvt_pk_bf16_f32 v5, v5, s0
	ds_write_b16 v2, v5
	v_mul_f32_e32 v5, 0xbfb8aa3b, v4
	v_exp_f32_e32 v5, v5
	s_nop 0
	v_mul_f32_e32 v3, v3, v5
	v_cvt_pk_bf16_f32 v3, v3, s0
	ds_write_b16 v2, v3 offset:34816
	v_mov_b32_e32 v2, s42
	v_mov_b32_e32 v3, s43
	v_cndmask_b32_e64 v2, v2, v3, s[6:7]
	v_mad_u64_u32 v[2:3], s[42:43], v2, s77, v[56:57]
	v_mov_b32_e32 v3, v163
	s_waitcnt lgkmcnt(0)
	v_lshlrev_b32_e32 v3, 16, v3
	v_mul_f32_e32 v3, 0xbfb8aa3b, v3
	v_exp_f32_e32 v3, v3
	s_nop 0
	v_add_f32_e32 v3, 1.0, v3
	v_div_scale_f32 v5, s[42:43], v3, v3, 1.0
	v_rcp_f32_e32 v6, v5
	s_nop 0
	v_fma_f32 v7, -v5, v6, 1.0
	v_fmac_f32_e32 v6, v7, v6
	v_div_scale_f32 v7, vcc, 1.0, v3, 1.0
	v_mul_f32_e32 v8, v7, v6
	v_fma_f32 v9, -v5, v8, v7
	v_fmac_f32_e32 v8, v9, v6
	v_fma_f32 v5, -v5, v8, v7
	v_div_fmas_f32 v5, v5, v6, v8
	v_div_fixup_f32 v3, v5, v3, 1.0
	v_fma_f32 v3, v1, v3, v0
	v_cmp_gt_f32_e32 vcc, s95, v3
	s_nop 1
	v_cndmask_b32_e64 v5, 0, 32, vcc
	v_ldexp_f32 v5, v3, v5
	v_log_f32_e32 v5, v5
	v_sub_f32_e32 v3, 1.0, v3
	v_mul_f32_e32 v6, 0x3f317217, v5
	v_fma_f32 v6, v5, s96, -v6
	v_fmac_f32_e32 v6, 0x3377d1cf, v5
	v_fmac_f32_e32 v6, 0x3f317217, v5
	v_cmp_lt_f32_e64 s[42:43], |v5|, s97
	s_nop 1
	v_cndmask_b32_e64 v5, v5, v6, s[42:43]
	v_cndmask_b32_e32 v6, 0, v209, vcc
	v_sub_f32_e32 v5, v5, v6
	v_add_f32_e32 v4, v4, v5
	v_mov_b32_e32 v5, v162
	v_mul_f32_e32 v6, 0x3fb8aa3b, v4
	v_exp_f32_e32 v6, v6
	s_add_i32 s42, s55, 3
	s_add_i32 s43, s47, 4
	s_waitcnt lgkmcnt(0)
	v_lshlrev_b32_e32 v5, 16, v5
	v_mul_f32_e32 v5, v6, v5
	v_cvt_pk_bf16_f32 v5, v5, s0
	ds_write_b16 v2, v5
	v_mul_f32_e32 v5, 0xbfb8aa3b, v4
	v_exp_f32_e32 v5, v5
	s_nop 0
	v_mul_f32_e32 v3, v3, v5
	v_cvt_pk_bf16_f32 v3, v3, s0
	ds_write_b16 v2, v3 offset:34816
	v_mov_b32_e32 v2, s42
	v_mov_b32_e32 v3, s43
	v_cndmask_b32_e64 v2, v2, v3, s[6:7]
	v_mad_u64_u32 v[2:3], s[42:43], v2, s77, v[56:57]
	v_mov_b32_e32 v3, v161
	s_waitcnt lgkmcnt(0)
	v_lshlrev_b32_e32 v3, 16, v3
	v_mul_f32_e32 v3, 0xbfb8aa3b, v3
	v_exp_f32_e32 v3, v3
	s_nop 0
	v_add_f32_e32 v3, 1.0, v3
	v_div_scale_f32 v5, s[42:43], v3, v3, 1.0
	v_rcp_f32_e32 v6, v5
	s_nop 0
	v_fma_f32 v7, -v5, v6, 1.0
	v_fmac_f32_e32 v6, v7, v6
	v_div_scale_f32 v7, vcc, 1.0, v3, 1.0
	v_mul_f32_e32 v8, v7, v6
	v_fma_f32 v9, -v5, v8, v7
	v_fmac_f32_e32 v8, v9, v6
	v_fma_f32 v5, -v5, v8, v7
	v_div_fmas_f32 v5, v5, v6, v8
	v_div_fixup_f32 v3, v5, v3, 1.0
	v_fma_f32 v3, v1, v3, v0
	v_cmp_gt_f32_e32 vcc, s95, v3
	s_nop 1
	v_cndmask_b32_e64 v5, 0, 32, vcc
	v_ldexp_f32 v5, v3, v5
	v_log_f32_e32 v5, v5
	v_sub_f32_e32 v3, 1.0, v3
	v_mul_f32_e32 v6, 0x3f317217, v5
	v_fma_f32 v6, v5, s96, -v6
	v_fmac_f32_e32 v6, 0x3377d1cf, v5
	v_fmac_f32_e32 v6, 0x3f317217, v5
	v_cmp_lt_f32_e64 s[42:43], |v5|, s97
	s_nop 1
	v_cndmask_b32_e64 v5, v5, v6, s[42:43]
	v_cndmask_b32_e32 v6, 0, v209, vcc
	v_sub_f32_e32 v5, v5, v6
	v_add_f32_e32 v4, v4, v5
	v_mov_b32_e32 v5, v160
	v_mul_f32_e32 v6, 0x3fb8aa3b, v4
	v_exp_f32_e32 v6, v6
	s_add_i32 s42, s55, 2
	s_add_i32 s43, s47, 5
	s_waitcnt lgkmcnt(0)
	v_lshlrev_b32_e32 v5, 16, v5
	v_mul_f32_e32 v5, v6, v5
	v_cvt_pk_bf16_f32 v5, v5, s0
	ds_write_b16 v2, v5
	v_mul_f32_e32 v5, 0xbfb8aa3b, v4
	v_exp_f32_e32 v5, v5
	s_nop 0
	v_mul_f32_e32 v3, v3, v5
	v_cvt_pk_bf16_f32 v3, v3, s0
	ds_write_b16 v2, v3 offset:34816
	v_mov_b32_e32 v2, s42
	v_mov_b32_e32 v3, s43
	v_cndmask_b32_e64 v2, v2, v3, s[6:7]
	v_mad_u64_u32 v[2:3], s[42:43], v2, s77, v[56:57]
	v_mov_b32_e32 v3, v159
	s_waitcnt lgkmcnt(0)
; DEVI float bf2f(u16 h) { return __uint_as_float(((unsigned)h) << 16); }
; DEVI float sigm(float x) { return 1.f / (1.f + __expf(-x)); }
; DEVI void hgrn_c_item(int TID_, int BID_, PREF p, int item, char* shm) {
;     ...
;     float run = 0.f;
; #pragma unroll 8
;     for (int s = 0; s < 64; ++s) {
;       const int i = dir == 0 ? s : 63 - s;
;       float f = lbv + (1.f - lbv) * sigm(bf2f(kc[i * 136]));
;       run += __logf(f);
;       qc[i * 136] = f2bf(bf2f(qc[i * 136]) * __expf(run));
;       kc[i * 136] = f2bf((1.f - f) * __expf(-run));
;     }
	v_lshlrev_b32_e32 v3, 16, v3
	v_mul_f32_e32 v3, 0xbfb8aa3b, v3
	v_exp_f32_e32 v3, v3
	s_nop 0
	v_add_f32_e32 v3, 1.0, v3
	v_div_scale_f32 v5, s[42:43], v3, v3, 1.0
	v_rcp_f32_e32 v6, v5
	s_nop 0
	v_fma_f32 v7, -v5, v6, 1.0
	v_fmac_f32_e32 v6, v7, v6
	v_div_scale_f32 v7, vcc, 1.0, v3, 1.0
	v_mul_f32_e32 v8, v7, v6
	v_fma_f32 v9, -v5, v8, v7
	v_fmac_f32_e32 v8, v9, v6
	v_fma_f32 v5, -v5, v8, v7
	v_div_fmas_f32 v5, v5, v6, v8
	v_div_fixup_f32 v3, v5, v3, 1.0
	v_fma_f32 v3, v1, v3, v0
	v_cmp_gt_f32_e32 vcc, s95, v3
	s_nop 1
	v_cndmask_b32_e64 v5, 0, 32, vcc
	v_ldexp_f32 v5, v3, v5
	v_log_f32_e32 v5, v5
	v_sub_f32_e32 v3, 1.0, v3
	v_mul_f32_e32 v6, 0x3f317217, v5
	v_fma_f32 v6, v5, s96, -v6
	v_fmac_f32_e32 v6, 0x3377d1cf, v5
	v_fmac_f32_e32 v6, 0x3f317217, v5
	v_cmp_lt_f32_e64 s[42:43], |v5|, s97
	s_nop 1
	v_cndmask_b32_e64 v5, v5, v6, s[42:43]
	v_cndmask_b32_e32 v6, 0, v209, vcc
	v_sub_f32_e32 v5, v5, v6
	v_add_f32_e32 v4, v4, v5
	v_mov_b32_e32 v5, v158
	v_mul_f32_e32 v6, 0x3fb8aa3b, v4
	v_exp_f32_e32 v6, v6
	s_add_i32 s42, s55, 1
	s_add_i32 s43, s47, 6
	s_waitcnt lgkmcnt(0)
	v_lshlrev_b32_e32 v5, 16, v5
	v_mul_f32_e32 v5, v6, v5
	v_cvt_pk_bf16_f32 v5, v5, s0
	ds_write_b16 v2, v5
	v_mul_f32_e32 v5, 0xbfb8aa3b, v4
	v_exp_f32_e32 v5, v5
	s_nop 0
	v_mul_f32_e32 v3, v3, v5
	v_cvt_pk_bf16_f32 v3, v3, s0
	ds_write_b16 v2, v3 offset:34816
	v_mov_b32_e32 v2, s42
	v_mov_b32_e32 v3, s43
	v_cndmask_b32_e64 v2, v2, v3, s[6:7]
	v_mad_u64_u32 v[2:3], s[42:43], v2, s77, v[56:57]
	v_mov_b32_e32 v3, v157
	s_waitcnt lgkmcnt(0)
	v_lshlrev_b32_e32 v3, 16, v3
	v_mul_f32_e32 v3, 0xbfb8aa3b, v3
	v_exp_f32_e32 v3, v3
	s_nop 0
	v_add_f32_e32 v3, 1.0, v3
	v_div_scale_f32 v5, s[42:43], v3, v3, 1.0
	v_rcp_f32_e32 v6, v5
	s_nop 0
	v_fma_f32 v7, -v5, v6, 1.0
	v_fmac_f32_e32 v6, v7, v6
	v_div_scale_f32 v7, vcc, 1.0, v3, 1.0
	v_mul_f32_e32 v8, v7, v6
	v_fma_f32 v9, -v5, v8, v7
	v_fmac_f32_e32 v8, v9, v6
	v_fma_f32 v5, -v5, v8, v7
	v_div_fmas_f32 v5, v5, v6, v8
	v_div_fixup_f32 v3, v5, v3, 1.0
	v_fma_f32 v3, v1, v3, v0
	v_cmp_gt_f32_e32 vcc, s95, v3
	s_nop 1
	v_cndmask_b32_e64 v5, 0, 32, vcc
	v_ldexp_f32 v5, v3, v5
	v_log_f32_e32 v5, v5
	v_sub_f32_e32 v3, 1.0, v3
	v_mul_f32_e32 v6, 0x3f317217, v5
	v_fma_f32 v6, v5, s96, -v6
	v_fmac_f32_e32 v6, 0x3377d1cf, v5
	v_fmac_f32_e32 v6, 0x3f317217, v5
	v_cmp_lt_f32_e64 s[42:43], |v5|, s97
	s_nop 1
	v_cndmask_b32_e64 v5, v5, v6, s[42:43]
	v_cndmask_b32_e32 v6, 0, v209, vcc
	v_sub_f32_e32 v5, v5, v6
	v_add_f32_e32 v6, v4, v5
	v_mov_b32_e32 v4, v156
	v_mul_f32_e32 v5, 0x3fb8aa3b, v6
	v_exp_f32_e32 v5, v5
	s_add_i32 s42, s47, 7
	s_add_i32 s47, s47, 8
	s_waitcnt lgkmcnt(0)
	v_lshlrev_b32_e32 v4, 16, v4
	v_mul_f32_e32 v4, v5, v4
	v_cvt_pk_bf16_f32 v4, v4, s0
	ds_write_b16 v2, v4
	v_mul_f32_e32 v4, 0xbfb8aa3b, v6
	v_exp_f32_e32 v4, v4
	s_nop 0
	v_mul_f32_e32 v3, v3, v4
	v_cvt_pk_bf16_f32 v3, v3, s0
	ds_write_b16 v2, v3 offset:34816
	v_mov_b32_e32 v2, s55
	v_mov_b32_e32 v3, s42
	v_cndmask_b32_e64 v2, v2, v3, s[6:7]
	v_mad_u64_u32 v[4:5], s[42:43], v2, s77, v[56:57]
	v_mov_b32_e32 v2, v155
	s_add_i32 s55, s55, -8
	s_cmp_lg_u32 s47, 64
	s_waitcnt lgkmcnt(0)
	v_lshlrev_b32_e32 v2, 16, v2
	v_mul_f32_e32 v2, 0xbfb8aa3b, v2
	v_exp_f32_e32 v2, v2
	s_nop 0
	v_add_f32_e32 v2, 1.0, v2
	v_div_scale_f32 v3, s[42:43], v2, v2, 1.0
	v_rcp_f32_e32 v5, v3
	s_nop 0
	v_fma_f32 v7, -v3, v5, 1.0
	v_fmac_f32_e32 v5, v7, v5
	v_div_scale_f32 v7, vcc, 1.0, v2, 1.0
	v_mul_f32_e32 v8, v7, v5
	v_fma_f32 v9, -v3, v8, v7
	v_fmac_f32_e32 v8, v9, v5
	v_fma_f32 v3, -v3, v8, v7
	v_div_fmas_f32 v3, v3, v5, v8
	v_div_fixup_f32 v2, v3, v2, 1.0
	v_fma_f32 v3, v1, v2, v0
	v_cmp_gt_f32_e32 vcc, s95, v3
	s_nop 1
	v_cndmask_b32_e64 v2, 0, 32, vcc
	v_ldexp_f32 v2, v3, v2
	v_log_f32_e32 v2, v2
	v_sub_f32_e32 v3, 1.0, v3
	v_mul_f32_e32 v5, 0x3f317217, v2
	v_fma_f32 v5, v2, s96, -v5
	v_fmac_f32_e32 v5, 0x3377d1cf, v2
	v_fmac_f32_e32 v5, 0x3f317217, v2
	v_cmp_lt_f32_e64 s[42:43], |v2|, s97
	s_nop 1
	v_cndmask_b32_e64 v2, v2, v5, s[42:43]
	v_cndmask_b32_e32 v5, 0, v209, vcc
	v_sub_f32_e32 v2, v2, v5
	v_add_f32_e32 v2, v6, v2
	v_mov_b32_e32 v5, v154
	v_mul_f32_e32 v6, 0x3fb8aa3b, v2
	v_exp_f32_e32 v6, v6
	s_waitcnt lgkmcnt(0)
	v_lshlrev_b32_e32 v5, 16, v5
	v_mul_f32_e32 v5, v6, v5
	v_cvt_pk_bf16_f32 v5, v5, s0
	ds_write_b16 v4, v5
	v_mul_f32_e32 v5, 0xbfb8aa3b, v2
	v_exp_f32_e32 v5, v5
	s_nop 0
	v_mul_f32_e32 v3, v3, v5
	v_cvt_pk_bf16_f32 v3, v3, s0
	ds_write_b16 v4, v3 offset:34816
	s_cbranch_scc1 .LBB0_197

; DEVI float bf2f(u16 h) { return __uint_as_float(((unsigned)h) << 16); }
; DEVI float sigm(float x) { return 1.f / (1.f + __expf(-x)); }
; DEVI void hgrn_a_item(int TID_, int BID_, PREF p, int item, char* shm) {
;     ...
;     float run = 0.f;
; #pragma unroll 8
;     for (int s = 0; s < 64; ++s) {
;       const int j = dir == 0 ? 63 - s : s;
;       float f = lbv + (1.f - lbv) * sigm(bf2f(zc[j * 136]));
;       dst[j] = f2bf((1.f - f) * __expf(run));
;       run += __logf(f);
;     }
;     dec[((size_t)(c * 8 + h) * 2 + dir) * 128 + d] = __expf(run);
.LBB0_460:
	s_add_i32 s38, s5, 7
	s_add_i32 s39, s4, 0
	v_mov_b32_e32 v235, s39
	v_mov_b32_e32 v234, s38
	v_cndmask_b32_e64 v235, v235, v234, s[52:53]
	v_mad_u32_u24 v233, v235, s77, v42
	ds_read_u16 v225, v233 offset:55296
	s_add_i32 s38, s5, 6
	s_add_i32 s39, s4, 1
	v_mov_b32_e32 v235, s39
	v_mov_b32_e32 v234, s38
	v_cndmask_b32_e64 v235, v235, v234, s[52:53]
	v_mad_u32_u24 v232, v235, s77, v42
	ds_read_u16 v224, v232 offset:55296
	s_add_i32 s38, s5, 5
	s_add_i32 s39, s4, 2
	v_mov_b32_e32 v235, s39
	v_mov_b32_e32 v234, s38
	v_cndmask_b32_e64 v235, v235, v234, s[52:53]
	v_mad_u32_u24 v231, v235, s77, v42
	ds_read_u16 v223, v231 offset:55296
	s_add_i32 s38, s5, 4
	s_add_i32 s39, s4, 3
	v_mov_b32_e32 v235, s39
	v_mov_b32_e32 v234, s38
	v_cndmask_b32_e64 v235, v235, v234, s[52:53]
	v_mad_u32_u24 v230, v235, s77, v42
	ds_read_u16 v222, v230 offset:55296
	s_add_i32 s38, s5, 3
	s_add_i32 s39, s4, 4
	v_mov_b32_e32 v235, s39
	v_mov_b32_e32 v234, s38
	v_cndmask_b32_e64 v235, v235, v234, s[52:53]
	v_mad_u32_u24 v229, v235, s77, v42
	ds_read_u16 v221, v229 offset:55296
	s_add_i32 s38, s5, 2
	s_add_i32 s39, s4, 5
	v_mov_b32_e32 v235, s39
	v_mov_b32_e32 v234, s38
	v_cndmask_b32_e64 v235, v235, v234, s[52:53]
	v_mad_u32_u24 v228, v235, s77, v42
	ds_read_u16 v220, v228 offset:55296
	s_add_i32 s38, s5, 1
	s_add_i32 s39, s4, 6
	v_mov_b32_e32 v235, s39
	v_mov_b32_e32 v234, s38
	v_cndmask_b32_e64 v235, v235, v234, s[52:53]
	v_mad_u32_u24 v227, v235, s77, v42
	ds_read_u16 v219, v227 offset:55296
	s_add_i32 s38, s5, 0
	s_add_i32 s39, s4, 7
	v_mov_b32_e32 v235, s39
	v_mov_b32_e32 v234, s38
	v_cndmask_b32_e64 v235, v235, v234, s[52:53]
	v_mad_u32_u24 v226, v235, s77, v42
	ds_read_u16 v218, v226 offset:55296
	s_waitcnt lgkmcnt(0)
	s_add_i32 s38, s5, 7
	v_mov_b32_e32 v3, s4
	v_mov_b32_e32 v4, s38
	v_cndmask_b32_e64 v3, v3, v4, s[52:53]
	v_mad_u64_u32 v[4:5], s[38:39], v3, s77, v[42:43]
	v_mov_b32_e32 v4, v225
	v_lshl_add_u32 v3, v3, 1, v143
	s_waitcnt lgkmcnt(0)
	v_lshlrev_b32_e32 v4, 16, v4
	v_mul_f32_e32 v4, 0xbfb8aa3b, v4
	v_exp_f32_e32 v4, v4
	s_nop 0
	v_add_f32_e32 v4, 1.0, v4
	v_div_scale_f32 v5, s[38:39], v4, v4, 1.0
	v_rcp_f32_e32 v6, v5
	s_add_i32 s38, s5, 6
	s_add_i32 s39, s4, 1
	v_fma_f32 v7, -v5, v6, 1.0
	v_fmac_f32_e32 v6, v7, v6
	v_div_scale_f32 v7, vcc, 1.0, v4, 1.0
	v_mul_f32_e32 v8, v7, v6
	v_fma_f32 v9, -v5, v8, v7
	v_fmac_f32_e32 v8, v9, v6
	v_fma_f32 v5, -v5, v8, v7
	v_div_fmas_f32 v5, v5, v6, v8
	v_mul_f32_e32 v6, 0x3fb8aa3b, v2
	v_exp_f32_e32 v6, v6
	v_div_fixup_f32 v4, v5, v4, 1.0
	v_fma_f32 v4, v1, v4, v0
	v_sub_f32_e32 v5, 1.0, v4
	v_mul_f32_e32 v5, v6, v5
	v_cvt_pk_bf16_f32 v5, v5, s0
	v_cmp_gt_f32_e32 vcc, s95, v4
	ds_write_b16 v3, v5 offset:18432
	s_nop 0
	v_cndmask_b32_e64 v3, 0, 32, vcc
	v_ldexp_f32 v3, v4, v3
	v_log_f32_e32 v3, v3
	s_nop 0
	v_mul_f32_e32 v4, 0x3f317217, v3
	v_fma_f32 v4, v3, s96, -v4
	v_fmac_f32_e32 v4, 0x3377d1cf, v3
	v_fmac_f32_e32 v4, 0x3f317217, v3
	v_cmp_lt_f32_e64 s[54:55], |v3|, s97
	s_nop 1
	v_cndmask_b32_e64 v3, v3, v4, s[54:55]
	v_cndmask_b32_e32 v4, 0, v209, vcc
	v_sub_f32_e32 v3, v3, v4
	v_add_f32_e32 v4, v2, v3
	v_mov_b32_e32 v2, s39
	v_mov_b32_e32 v3, s38
	v_cndmask_b32_e64 v5, v2, v3, s[52:53]
	v_mad_u64_u32 v[2:3], s[38:39], v5, s77, v[42:43]
	v_mov_b32_e32 v2, v224
	v_lshl_add_u32 v5, v5, 1, v143
	s_waitcnt lgkmcnt(0)
	v_lshlrev_b32_e32 v2, 16, v2
	v_mul_f32_e32 v2, 0xbfb8aa3b, v2
	v_exp_f32_e32 v2, v2
	s_nop 0
	v_add_f32_e32 v2, 1.0, v2
	v_div_scale_f32 v3, s[38:39], v2, v2, 1.0
	v_rcp_f32_e32 v6, v3
	s_add_i32 s38, s5, 5
	s_add_i32 s39, s4, 2
	v_fma_f32 v7, -v3, v6, 1.0
	v_fmac_f32_e32 v6, v7, v6
	v_div_scale_f32 v7, vcc, 1.0, v2, 1.0
	v_mul_f32_e32 v8, v7, v6
	v_fma_f32 v9, -v3, v8, v7
	v_fmac_f32_e32 v8, v9, v6
	v_fma_f32 v3, -v3, v8, v7
	v_div_fmas_f32 v3, v3, v6, v8
	v_mul_f32_e32 v6, 0x3fb8aa3b, v4
	v_exp_f32_e32 v6, v6
	v_div_fixup_f32 v2, v3, v2, 1.0
	v_fma_f32 v2, v1, v2, v0
	v_sub_f32_e32 v3, 1.0, v2
	v_mul_f32_e32 v3, v6, v3
	v_cvt_pk_bf16_f32 v3, v3, s0
	v_cmp_gt_f32_e32 vcc, s95, v2
	ds_write_b16 v5, v3 offset:18432
	s_nop 0
	v_cndmask_b32_e64 v3, 0, 32, vcc
	v_ldexp_f32 v2, v2, v3
	v_log_f32_e32 v2, v2
	s_nop 0
	v_mul_f32_e32 v3, 0x3f317217, v2
	v_fma_f32 v3, v2, s96, -v3
	v_fmac_f32_e32 v3, 0x3377d1cf, v2
	v_fmac_f32_e32 v3, 0x3f317217, v2
	v_cmp_lt_f32_e64 s[54:55], |v2|, s97
	s_nop 1
	v_cndmask_b32_e64 v2, v2, v3, s[54:55]
	v_cndmask_b32_e32 v3, 0, v209, vcc
	v_sub_f32_e32 v2, v2, v3
	v_add_f32_e32 v4, v4, v2
	v_mov_b32_e32 v2, s39
	v_mov_b32_e32 v3, s38
	v_cndmask_b32_e64 v5, v2, v3, s[52:53]
	v_mad_u64_u32 v[2:3], s[38:39], v5, s77, v[42:43]
	v_mov_b32_e32 v2, v223
	v_lshl_add_u32 v5, v5, 1, v143
	s_waitcnt lgkmcnt(0)
	v_lshlrev_b32_e32 v2, 16, v2
	v_mul_f32_e32 v2, 0xbfb8aa3b, v2
	v_exp_f32_e32 v2, v2
	s_nop 0
	v_add_f32_e32 v2, 1.0, v2
	v_div_scale_f32 v3, s[38:39], v2, v2, 1.0
	v_rcp_f32_e32 v6, v3
	s_add_i32 s38, s5, 4
	s_add_i32 s39, s4, 3
	v_fma_f32 v7, -v3, v6, 1.0
	v_fmac_f32_e32 v6, v7, v6
	v_div_scale_f32 v7, vcc, 1.0, v2, 1.0
	v_mul_f32_e32 v8, v7, v6
	v_fma_f32 v9, -v3, v8, v7
	v_fmac_f32_e32 v8, v9, v6
	v_fma_f32 v3, -v3, v8, v7
	v_div_fmas_f32 v3, v3, v6, v8
	v_mul_f32_e32 v6, 0x3fb8aa3b, v4
	v_exp_f32_e32 v6, v6
	v_div_fixup_f32 v2, v3, v2, 1.0
	v_fma_f32 v2, v1, v2, v0
	v_sub_f32_e32 v3, 1.0, v2
	v_mul_f32_e32 v3, v6, v3
	v_cvt_pk_bf16_f32 v3, v3, s0
	v_cmp_gt_f32_e32 vcc, s95, v2
	ds_write_b16 v5, v3 offset:18432
	s_nop 0
	v_cndmask_b32_e64 v3, 0, 32, vcc
	v_ldexp_f32 v2, v2, v3
	v_log_f32_e32 v2, v2
	s_nop 0
	v_mul_f32_e32 v3, 0x3f317217, v2
	v_fma_f32 v3, v2, s96, -v3
	v_fmac_f32_e32 v3, 0x3377d1cf, v2
	v_fmac_f32_e32 v3, 0x3f317217, v2
	v_cmp_lt_f32_e64 s[54:55], |v2|, s97
	s_nop 1
	v_cndmask_b32_e64 v2, v2, v3, s[54:55]
	v_cndmask_b32_e32 v3, 0, v209, vcc
	v_sub_f32_e32 v2, v2, v3
	v_add_f32_e32 v4, v4, v2
	v_mov_b32_e32 v2, s39
	v_mov_b32_e32 v3, s38
	v_cndmask_b32_e64 v5, v2, v3, s[52:53]
	v_mad_u64_u32 v[2:3], s[38:39], v5, s77, v[42:43]
	v_mov_b32_e32 v2, v222
	v_lshl_add_u32 v5, v5, 1, v143
	s_waitcnt lgkmcnt(0)
; DEVI float bf2f(u16 h) { return __uint_as_float(((unsigned)h) << 16); }
; DEVI float sigm(float x) { return 1.f / (1.f + __expf(-x)); }
; DEVI void hgrn_a_item(int TID_, int BID_, PREF p, int item, char* shm) {
;     ...
;     float run = 0.f;
; #pragma unroll 8
;     for (int s = 0; s < 64; ++s) {
;       const int j = dir == 0 ? 63 - s : s;
;       float f = lbv + (1.f - lbv) * sigm(bf2f(zc[j * 136]));
;       dst[j] = f2bf((1.f - f) * __expf(run));
;       run += __logf(f);
;     }
;     dec[((size_t)(c * 8 + h) * 2 + dir) * 128 + d] = __expf(run);
	v_lshlrev_b32_e32 v2, 16, v2
	v_mul_f32_e32 v2, 0xbfb8aa3b, v2
	v_exp_f32_e32 v2, v2
	s_nop 0
	v_add_f32_e32 v2, 1.0, v2
	v_div_scale_f32 v3, s[38:39], v2, v2, 1.0
	v_rcp_f32_e32 v6, v3
	s_add_i32 s38, s5, 3
	s_add_i32 s39, s4, 4
	v_fma_f32 v7, -v3, v6, 1.0
	v_fmac_f32_e32 v6, v7, v6
	v_div_scale_f32 v7, vcc, 1.0, v2, 1.0
	v_mul_f32_e32 v8, v7, v6
	v_fma_f32 v9, -v3, v8, v7
	v_fmac_f32_e32 v8, v9, v6
	v_fma_f32 v3, -v3, v8, v7
	v_div_fmas_f32 v3, v3, v6, v8
	v_mul_f32_e32 v6, 0x3fb8aa3b, v4
	v_exp_f32_e32 v6, v6
	v_div_fixup_f32 v2, v3, v2, 1.0
	v_fma_f32 v2, v1, v2, v0
	v_sub_f32_e32 v3, 1.0, v2
	v_mul_f32_e32 v3, v6, v3
	v_cvt_pk_bf16_f32 v3, v3, s0
	v_cmp_gt_f32_e32 vcc, s95, v2
	ds_write_b16 v5, v3 offset:18432
	s_nop 0
	v_cndmask_b32_e64 v3, 0, 32, vcc
	v_ldexp_f32 v2, v2, v3
	v_log_f32_e32 v2, v2
	s_nop 0
	v_mul_f32_e32 v3, 0x3f317217, v2
	v_fma_f32 v3, v2, s96, -v3
	v_fmac_f32_e32 v3, 0x3377d1cf, v2
	v_fmac_f32_e32 v3, 0x3f317217, v2
	v_cmp_lt_f32_e64 s[54:55], |v2|, s97
	s_nop 1
	v_cndmask_b32_e64 v2, v2, v3, s[54:55]
	v_cndmask_b32_e32 v3, 0, v209, vcc
	v_sub_f32_e32 v2, v2, v3
	v_add_f32_e32 v4, v4, v2
	v_mov_b32_e32 v2, s39
	v_mov_b32_e32 v3, s38
	v_cndmask_b32_e64 v5, v2, v3, s[52:53]
	v_mad_u64_u32 v[2:3], s[38:39], v5, s77, v[42:43]
	v_mov_b32_e32 v2, v221
	v_lshl_add_u32 v5, v5, 1, v143
	s_waitcnt lgkmcnt(0)
	v_lshlrev_b32_e32 v2, 16, v2
	v_mul_f32_e32 v2, 0xbfb8aa3b, v2
	v_exp_f32_e32 v2, v2
	s_nop 0
	v_add_f32_e32 v2, 1.0, v2
	v_div_scale_f32 v3, s[38:39], v2, v2, 1.0
	v_rcp_f32_e32 v6, v3
	s_add_i32 s38, s5, 2
	s_add_i32 s39, s4, 5
	v_fma_f32 v7, -v3, v6, 1.0
	v_fmac_f32_e32 v6, v7, v6
	v_div_scale_f32 v7, vcc, 1.0, v2, 1.0
	v_mul_f32_e32 v8, v7, v6
	v_fma_f32 v9, -v3, v8, v7
	v_fmac_f32_e32 v8, v9, v6
	v_fma_f32 v3, -v3, v8, v7
	v_div_fmas_f32 v3, v3, v6, v8
	v_mul_f32_e32 v6, 0x3fb8aa3b, v4
	v_exp_f32_e32 v6, v6
	v_div_fixup_f32 v2, v3, v2, 1.0
	v_fma_f32 v2, v1, v2, v0
	v_sub_f32_e32 v3, 1.0, v2
	v_mul_f32_e32 v3, v6, v3
	v_cvt_pk_bf16_f32 v3, v3, s0
	v_cmp_gt_f32_e32 vcc, s95, v2
	ds_write_b16 v5, v3 offset:18432
	s_nop 0
	v_cndmask_b32_e64 v3, 0, 32, vcc
	v_ldexp_f32 v2, v2, v3
	v_log_f32_e32 v2, v2
	s_nop 0
	v_mul_f32_e32 v3, 0x3f317217, v2
	v_fma_f32 v3, v2, s96, -v3
	v_fmac_f32_e32 v3, 0x3377d1cf, v2
	v_fmac_f32_e32 v3, 0x3f317217, v2
	v_cmp_lt_f32_e64 s[54:55], |v2|, s97
	s_nop 1
	v_cndmask_b32_e64 v2, v2, v3, s[54:55]
	v_cndmask_b32_e32 v3, 0, v209, vcc
	v_sub_f32_e32 v2, v2, v3
	v_add_f32_e32 v4, v4, v2
	v_mov_b32_e32 v2, s39
	v_mov_b32_e32 v3, s38
	v_cndmask_b32_e64 v5, v2, v3, s[52:53]
	v_mad_u64_u32 v[2:3], s[38:39], v5, s77, v[42:43]
	v_mov_b32_e32 v2, v220
	v_lshl_add_u32 v5, v5, 1, v143
	s_waitcnt lgkmcnt(0)
	v_lshlrev_b32_e32 v2, 16, v2
	v_mul_f32_e32 v2, 0xbfb8aa3b, v2
	v_exp_f32_e32 v2, v2
	s_nop 0
	v_add_f32_e32 v2, 1.0, v2
	v_div_scale_f32 v3, s[38:39], v2, v2, 1.0
	v_rcp_f32_e32 v6, v3
	s_add_i32 s38, s5, 1
	s_add_i32 s39, s4, 6
	v_fma_f32 v7, -v3, v6, 1.0
	v_fmac_f32_e32 v6, v7, v6
	v_div_scale_f32 v7, vcc, 1.0, v2, 1.0
	v_mul_f32_e32 v8, v7, v6
	v_fma_f32 v9, -v3, v8, v7
	v_fmac_f32_e32 v8, v9, v6
	v_fma_f32 v3, -v3, v8, v7
	v_div_fmas_f32 v3, v3, v6, v8
	v_mul_f32_e32 v6, 0x3fb8aa3b, v4
	v_exp_f32_e32 v6, v6
	v_div_fixup_f32 v2, v3, v2, 1.0
	v_fma_f32 v2, v1, v2, v0
	v_sub_f32_e32 v3, 1.0, v2
	v_mul_f32_e32 v3, v6, v3
	v_cvt_pk_bf16_f32 v3, v3, s0
	v_cmp_gt_f32_e32 vcc, s95, v2
	ds_write_b16 v5, v3 offset:18432
	s_nop 0
	v_cndmask_b32_e64 v3, 0, 32, vcc
	v_ldexp_f32 v2, v2, v3
	v_log_f32_e32 v2, v2
	s_nop 0
	v_mul_f32_e32 v3, 0x3f317217, v2
	v_fma_f32 v3, v2, s96, -v3
	v_fmac_f32_e32 v3, 0x3377d1cf, v2
	v_fmac_f32_e32 v3, 0x3f317217, v2
	v_cmp_lt_f32_e64 s[54:55], |v2|, s97
	s_nop 1
	v_cndmask_b32_e64 v2, v2, v3, s[54:55]
	v_cndmask_b32_e32 v3, 0, v209, vcc
	v_sub_f32_e32 v2, v2, v3
	v_add_f32_e32 v4, v4, v2
	v_mov_b32_e32 v2, s39
	v_mov_b32_e32 v3, s38
	v_cndmask_b32_e64 v5, v2, v3, s[52:53]
	v_mad_u64_u32 v[2:3], s[38:39], v5, s77, v[42:43]
	v_mov_b32_e32 v2, v219
	v_lshl_add_u32 v5, v5, 1, v143
	s_waitcnt lgkmcnt(0)
	v_lshlrev_b32_e32 v2, 16, v2
	v_mul_f32_e32 v2, 0xbfb8aa3b, v2
	v_exp_f32_e32 v2, v2
	s_nop 0
	v_add_f32_e32 v2, 1.0, v2
	v_div_scale_f32 v3, s[38:39], v2, v2, 1.0
	v_rcp_f32_e32 v6, v3
	s_add_i32 s38, s4, 7
	s_add_i32 s4, s4, 8
	v_fma_f32 v7, -v3, v6, 1.0
	v_fmac_f32_e32 v6, v7, v6
	v_div_scale_f32 v7, vcc, 1.0, v2, 1.0
	v_mul_f32_e32 v8, v7, v6
	v_fma_f32 v9, -v3, v8, v7
	v_fmac_f32_e32 v8, v9, v6
	v_fma_f32 v3, -v3, v8, v7
	v_div_fmas_f32 v3, v3, v6, v8
	v_mul_f32_e32 v6, 0x3fb8aa3b, v4
	v_exp_f32_e32 v6, v6
	v_div_fixup_f32 v2, v3, v2, 1.0
	v_fma_f32 v2, v1, v2, v0
	v_sub_f32_e32 v3, 1.0, v2
	v_mul_f32_e32 v3, v6, v3
	v_cvt_pk_bf16_f32 v3, v3, s0
	v_cmp_gt_f32_e32 vcc, s95, v2
	ds_write_b16 v5, v3 offset:18432
	s_nop 0
	v_cndmask_b32_e64 v3, 0, 32, vcc
	v_ldexp_f32 v2, v2, v3
	v_log_f32_e32 v2, v2
	s_nop 0
	v_mul_f32_e32 v3, 0x3f317217, v2
	v_fma_f32 v3, v2, s96, -v3
	v_fmac_f32_e32 v3, 0x3377d1cf, v2
	v_fmac_f32_e32 v3, 0x3f317217, v2
	v_cmp_lt_f32_e64 s[54:55], |v2|, s97
	s_nop 1
	v_cndmask_b32_e64 v2, v2, v3, s[54:55]
	v_cndmask_b32_e32 v3, 0, v209, vcc
	v_sub_f32_e32 v2, v2, v3
	v_add_f32_e32 v4, v4, v2
	v_mov_b32_e32 v2, s38
	v_mov_b32_e32 v3, s5
	v_cndmask_b32_e64 v5, v2, v3, s[52:53]
	v_mad_u64_u32 v[2:3], s[38:39], v5, s77, v[42:43]
	v_mov_b32_e32 v2, v218
	v_lshl_add_u32 v5, v5, 1, v143
	s_add_i32 s5, s5, -8
	s_cmp_eq_u32 s4, 64
	s_waitcnt lgkmcnt(0)
	v_lshlrev_b32_e32 v2, 16, v2
	v_mul_f32_e32 v2, 0xbfb8aa3b, v2
	v_exp_f32_e32 v2, v2
	s_nop 0
	v_add_f32_e32 v2, 1.0, v2
	v_div_scale_f32 v3, s[38:39], v2, v2, 1.0
	v_rcp_f32_e32 v6, v3
	s_nop 0
	v_fma_f32 v7, -v3, v6, 1.0
	v_fmac_f32_e32 v6, v7, v6
	v_div_scale_f32 v7, vcc, 1.0, v2, 1.0
	v_mul_f32_e32 v8, v7, v6
	v_fma_f32 v9, -v3, v8, v7
	v_fmac_f32_e32 v8, v9, v6
	v_fma_f32 v3, -v3, v8, v7
	v_div_fmas_f32 v3, v3, v6, v8
	v_mul_f32_e32 v6, 0x3fb8aa3b, v4
	v_exp_f32_e32 v6, v6
	v_div_fixup_f32 v2, v3, v2, 1.0
	v_fma_f32 v2, v1, v2, v0
	v_sub_f32_e32 v3, 1.0, v2
	v_mul_f32_e32 v3, v6, v3
	v_cvt_pk_bf16_f32 v3, v3, s0
	v_cmp_gt_f32_e32 vcc, s95, v2
	ds_write_b16 v5, v3 offset:18432
	s_nop 0
	v_cndmask_b32_e64 v3, 0, 32, vcc
	v_ldexp_f32 v2, v2, v3
	v_log_f32_e32 v2, v2
	s_nop 0
	v_mul_f32_e32 v3, 0x3f317217, v2
	v_fma_f32 v3, v2, s96, -v3
	v_fmac_f32_e32 v3, 0x3377d1cf, v2
	v_fmac_f32_e32 v3, 0x3f317217, v2
	v_cmp_lt_f32_e64 s[54:55], |v2|, s97
	s_nop 1
	v_cndmask_b32_e64 v2, v2, v3, s[54:55]
	v_cndmask_b32_e32 v3, 0, v209, vcc
	v_sub_f32_e32 v2, v2, v3
	v_add_f32_e32 v2, v4, v2
	s_cbranch_scc0 .LBB0_460
	v_mul_f32_e32 v0, 0x3fb8aa3b, v2
	v_exp_f32_e32 v2, v0
	s_ashr_i32 s41, s40, 31
	s_lshl_b64 s[4:5], s[40:41], 10
	v_lshl_add_u64 v[0:1], v[44:45], 0, s[4:5]
	global_store_dword v[0:1], v2, off
	v_mov_b64_e32 v[0:1], s[40:41]

; DEVI void sub_barrier(unsigned* cnt, unsigned target, int tid) {
;   asm volatile("s_waitcnt vmcnt(0)" ::: "memory");
;   __syncthreads();
;   if (tid == 0) {
;     __builtin_amdgcn_fence(__ATOMIC_RELEASE, "agent");
;     asm volatile("s_waitcnt vmcnt(0)" ::: "memory");
;     __hip_atomic_fetch_add(cnt, 1u, __ATOMIC_RELAXED, __HIP_MEMORY_SCOPE_AGENT);
; __global__ __launch_bounds__(512, 2) void mega(Params p_arg, int lo, int hi) {
;     ...
;     if (hi - lo > 1) {
;       if (ph == 0) grid.sync();
;       else sub_barrier((unsigned*)(ws + OFF_CNT) + 128, (unsigned)gridDim.x * (unsigned)ph, TID_);
.LBB0_728:
	s_and_b64 vcc, exec, s[36:37]
	s_cbranch_vccz .LBB0_745
	s_mov_b32 s4, 0x40100400
	s_mov_b32 s5, 0x24120900
	s_mov_b32 s7, 0x48
	s_cmp_lt_u32 s58, 64
	s_cbranch_scc1 .Lsk_lo
	s_sub_u32 s6, s58, 64
	s_lshr_b32 s7, s7, s6
	s_branch .Lsk_test
.Lsk_lo:
	s_lshr_b64 s[4:5], s[4:5], s58
	s_mov_b32 s7, s4
.Lsk_test:
	s_and_b32 s7, s7, 1
	s_cmp_eq_u32 s7, 0
	s_cbranch_scc1 .Lsk_no
	v_readlane_b32 s6, v236, 63
	s_nop 3
	s_add_i32 s6, s6, -1
	s_nop 0
	v_writelane_b32 v236, s6, 63
	s_branch .Lskip_bar
.Lsk_no:
	s_waitcnt vmcnt(0)
	v_cmp_eq_u32_e32 vcc, 0, v198
	s_waitcnt lgkmcnt(0)
	s_barrier
	s_and_saveexec_b64 s[12:13], vcc
	s_cbranch_execz .LBB0_747
	s_mov_b64 s[6:7], exec
	buffer_wbl2 sc1
	s_waitcnt vmcnt(0)
	s_waitcnt vmcnt(0)
	v_mbcnt_lo_u32_b32 v0, s6, 0
	s_add_u32 s4, s84, 0xcab1200
	v_mbcnt_hi_u32_b32 v0, s7, v0
	s_addc_u32 s5, s85, 0
	v_cmp_eq_u32_e32 vcc, 0, v0
	s_and_saveexec_b64 s[8:9], vcc
	s_cbranch_execz .LBB0_732
	s_bcnt1_i32_b64 s6, s[6:7]
	v_mov_b32_e32 v0, s6
	global_atomic_add v197, v0, s[4:5]
.LBB0_732:
	s_or_b64 exec, exec, s[8:9]
	v_readlane_b32 s8, v236, 63
	s_nop 3
	s_add_i32 s8, s8, s58
	s_mul_i32 s8, s8, s66
	s_mov_b32 s9, 0x1000000
	s_branch .LBB0_735

; DEVI void sub_barrier(unsigned* cnt, unsigned target, int tid) {
;     ...
;     unsigned spins = 0;
;     while (__hip_atomic_load(cnt, __ATOMIC_RELAXED, __HIP_MEMORY_SCOPE_AGENT) < target) {
;       __builtin_amdgcn_s_sleep(4);
;       if (++spins > (1u << 24)) break;
;     }
.LBB0_735:
	global_load_dword v0, v197, s[4:5] sc1
	s_mov_b64 s[6:7], -1
	s_waitcnt vmcnt(0)
	v_cmp_le_u32_e32 vcc, s8, v0
	s_cbranch_vccnz .LBB0_734
	s_cmp_lg_u32 s9, 0
	s_sleep 120
	s_cbranch_scc0 .LBB0_733
	global_load_dword v0, v197, s[4:5] sc1
	s_waitcnt vmcnt(0)
	v_cmp_gt_u32_e32 vcc, s8, v0
	s_cbranch_vccz .LBB0_734
	s_sleep 120
	global_load_dword v0, v197, s[4:5] sc1
	s_waitcnt vmcnt(0)
	v_cmp_gt_u32_e32 vcc, s8, v0
	s_cbranch_vccz .LBB0_734
	s_sleep 120
	global_load_dword v0, v197, s[4:5] sc1
	s_waitcnt vmcnt(0)
	v_cmp_gt_u32_e32 vcc, s8, v0
	s_cbranch_vccz .LBB0_734
	s_sleep 120
	global_load_dword v0, v197, s[4:5] sc1
	s_waitcnt vmcnt(0)
	v_cmp_gt_u32_e32 vcc, s8, v0
	s_cbranch_vccz .LBB0_734
	s_sleep 120
	global_load_dword v0, v197, s[4:5] sc1
	s_waitcnt vmcnt(0)
	v_cmp_gt_u32_e32 vcc, s8, v0
	s_cbranch_vccz .LBB0_734
	s_sleep 120
	global_load_dword v0, v197, s[4:5] sc1
	s_waitcnt vmcnt(0)
	v_cmp_gt_u32_e32 vcc, s8, v0
	s_cbranch_vccz .LBB0_734
	s_sleep 120
	global_load_dword v0, v197, s[4:5] sc1
	s_waitcnt vmcnt(0)
	v_cmp_gt_u32_e32 vcc, s8, v0
	s_cbranch_vccz .LBB0_734
	s_sleep 120
	s_add_i32 s9, s9, -8
	s_mov_b64 s[6:7], 0
	s_branch .LBB0_734

; __global__ __launch_bounds__(512, 2) void mega(Params p_arg, int lo, int hi) {
;     ...
;     if (hi - lo > 1) {
;       if (ph == 0) grid.sync();
;       else sub_barrier((unsigned*)(ws + OFF_CNT) + 128, (unsigned)gridDim.x * (unsigned)ph, TID_);
;     }
;     ...
;   }
.Lskip_bar:
	s_getpc_b64 s[98:99]
